# hand-written convert_layer_weights: per-wave streaming 64x32 tiles, 16B loads/stores, no barriers
# baseline (speedup 1.0000x reference)
; __device__ __forceinline__ float lo2f(unsigned u) { return __uint_as_float(u << 16); }
; __device__ __forceinline__ float hi2f(unsigned u) { return __uint_as_float(u & 0xffff0000u); }
; __device__ __forceinline__ void rwkv_prep_task(KP p, int l, int tile, int hg, bf16_t* sAp) {
;     ...
;     const int R = row0 + fr;
;     bool first; int sb = 0;
;     if (!samp) first = (R & 2047) == 0; else { const int rs = R - TPROMPT; first = (rs & 7) == 0; sb = rs >> 3; }
;     const int cb = h * 64 + fq * 16;
;     float x3[3][16];
; #pragma unroll
;     for (int q = 0; q < 3; ++q) {
;         const int col = q * 512 + cb;
;         const u32x4 c0 = *(const u32x4*)(P + (size_t)R * PW + col), c1 = *(const u32x4*)(P + (size_t)R * PW + col + 8);
;         const u32x4 p0 = *(const u32x4*)(P + (size_t)(R > 0 ? R - 1 : 0) * PW + col), p1 = *(const u32x4*)(P + (size_t)(R > 0 ? R - 1 : 0) * PW + col + 8);
; #pragma unroll
;         for (int e4 = 0; e4 < 4; ++e4) {
;             const float4 su = *(const float4*)(shs + (size_t)sb * 1792 + col + e4 * 4);
;             const float4 m4 = *(const float4*)(mu + col + e4 * 4);
;             const float sv[4] = {su.x, su.y, su.z, su.w}, mm[4] = {m4.x, m4.y, m4.z, m4.w};
; #pragma unroll
;             for (int k = 0; k < 4; ++k) {
;                 const int e = e4 * 4 + k;
;                 const unsigned cu = e < 8 ? c0[e >> 1] : c1[(e - 8) >> 1], pu = e < 8 ? p0[e >> 1] : p1[(e - 8) >> 1];
;                 const float cv = (e & 1) ? hi2f(cu) : lo2f(cu), pp = (e & 1) ? hi2f(pu) : lo2f(pu);
;                 const float prev = first ? (samp ? sv[k] : 0.f) : pp;
;                 x3[q][e] = cv + (prev - cv) * mm[k];
;             }
;         }
;     }
.LBB0_419:
	v_or_b32_e32 v156, v74, v12
	v_max_i32_e32 v12, 1, v154
	v_mov_b64_e32 v[52:53], s[8:9]
	v_add_u32_e32 v12, -1, v12
	v_ashrrev_i32_e32 v157, 31, v156
	v_mad_i64_i32 v[54:55], s[12:13], v154, s92, v[52:53]
	v_mad_u64_u32 v[52:53], s[12:13], v12, s92, v[52:53]
	v_lshl_add_u64 v[50:51], v[50:51], 2, s[18:19]
	v_lshlrev_b64 v[56:57], 1, v[156:157]
	v_lshlrev_b64 v[86:87], 2, v[156:157]
	v_lshl_add_u64 v[88:89], v[54:55], 0, v[56:57]
	v_lshl_add_u64 v[90:91], v[52:53], 0, v[56:57]
	v_lshl_add_u64 v[82:83], v[50:51], 0, v[86:87]
	global_load_dwordx4 v[94:97], v[88:89], off
	global_load_dwordx4 v[98:101], v[90:91], off
	global_load_dwordx4 v[102:105], v[82:83], off
	global_load_dwordx4 v[106:109], v[82:83], off offset:16
	v_lshl_add_u64 v[84:85], s[44:45], 0, v[86:87]
	global_load_dwordx4 v[110:113], v[84:85], off
	global_load_dwordx4 v[114:117], v[84:85], off offset:16
	global_load_dwordx4 v[50:53], v[88:89], off offset:16
	global_load_dwordx4 v[54:57], v[90:91], off offset:16
	global_load_dwordx4 v[78:81], v[82:83], off offset:32
	global_load_dwordx4 v[74:77], v[84:85], off offset:32
	global_load_dwordx4 v[118:121], v[82:83], off offset:48
	global_load_dwordx4 v[122:125], v[84:85], off offset:48
	global_load_dwordx4 v[58:61], v[88:89], off offset:2064
	global_load_dwordx4 v[66:69], v[88:89], off offset:2048
	global_load_dwordx4 v[62:65], v[90:91], off offset:2064
	global_load_dwordx4 v[70:73], v[90:91], off offset:2048
	v_add_co_u32_e32 v126, vcc, s27, v82
	s_mov_b64 s[12:13], 0x1000
	s_nop 0
	v_addc_co_u32_e32 v127, vcc, 0, v83, vcc
	v_add_co_u32_e32 v130, vcc, s27, v84
	s_mov_b32 s2, 0x7f800000
	s_nop 0
	v_addc_co_u32_e32 v131, vcc, 0, v85, vcc
	global_load_dwordx4 v[126:129], v[126:127], off
	s_nop 0
	global_load_dwordx4 v[130:133], v[130:131], off
	v_cmp_eq_u32_e32 vcc, 0, v92
	v_ashrrev_i32_e32 v155, 31, v154
	v_cvt_pk_bf16_f32 v39, v27, v39
	v_cvt_pk_bf16_f32 v29, v29, v41
	s_waitcnt vmcnt(17)
	v_lshlrev_b32_e32 v172, 16, v94
	s_waitcnt vmcnt(16)
	v_lshlrev_b32_e32 v12, 16, v98
	s_waitcnt vmcnt(15)
	v_cndmask_b32_e64 v93, v102, 0, s[40:41]
	v_and_b32_e32 v174, 0xffff0000, v94
	v_and_b32_e32 v94, 0xffff0000, v98
	v_cndmask_b32_e64 v98, v103, 0, s[40:41]
	v_lshlrev_b32_e32 v173, 16, v95
	v_lshlrev_b32_e32 v102, 16, v99
	v_cndmask_b32_e64 v103, v104, 0, s[40:41]
	v_and_b32_e32 v176, 0xffff0000, v95
	v_and_b32_e32 v95, 0xffff0000, v99
	v_cndmask_b32_e64 v99, v105, 0, s[40:41]
	v_lshlrev_b32_e32 v175, 16, v96
	v_lshlrev_b32_e32 v104, 16, v100
	s_waitcnt vmcnt(14)
	v_cndmask_b32_e64 v105, v106, 0, s[40:41]
	v_and_b32_e32 v177, 0xffff0000, v96
	v_and_b32_e32 v96, 0xffff0000, v100
	v_cndmask_b32_e64 v100, v107, 0, s[40:41]
	v_lshlrev_b32_e32 v106, 16, v101
	v_cndmask_b32_e64 v107, v108, 0, s[40:41]
	v_cndmask_b32_e32 v12, v12, v93, vcc
	v_cndmask_b32_e32 v92, v94, v98, vcc
	v_cndmask_b32_e32 v94, v95, v99, vcc
	v_cndmask_b32_e32 v95, v104, v105, vcc
	v_cndmask_b32_e32 v96, v96, v100, vcc
	v_lshlrev_b32_e32 v168, 16, v97
	v_cndmask_b32_e32 v98, v106, v107, vcc
	v_sub_f32_e32 v12, v12, v172
	v_sub_f32_e32 v95, v95, v175
	v_sub_f32_e32 v96, v96, v177
	v_and_b32_e32 v171, 0xffff0000, v97
	v_and_b32_e32 v97, 0xffff0000, v101
	v_sub_f32_e32 v98, v98, v168
	s_waitcnt vmcnt(13)
	v_fmac_f32_e32 v172, v12, v110
	s_waitcnt vmcnt(12)
	v_fmac_f32_e32 v175, v95, v114
	v_fmac_f32_e32 v177, v96, v115
	v_cndmask_b32_e64 v12, v109, 0, s[40:41]
	v_lshl_add_u64 v[114:115], v[82:83], 0, s[12:13]
	v_cndmask_b32_e32 v93, v102, v103, vcc
	v_fmac_f32_e32 v168, v98, v116
	v_cndmask_b32_e32 v12, v97, v12, vcc
	global_load_dwordx4 v[98:101], v[114:115], off offset:32
	global_load_dwordx4 v[102:105], v[114:115], off offset:16
	v_sub_f32_e32 v12, v12, v171
	v_sub_f32_e32 v92, v92, v174
	v_sub_f32_e32 v93, v93, v173
	v_sub_f32_e32 v94, v94, v176
	v_fmac_f32_e32 v171, v12, v117
	v_lshl_add_u64 v[116:117], v[84:85], 0, s[12:13]
	v_fmac_f32_e32 v174, v92, v111
	v_fmac_f32_e32 v173, v93, v112
	v_fmac_f32_e32 v176, v94, v113
	global_load_dwordx4 v[106:109], v[116:117], off offset:32
	global_load_dwordx4 v[110:113], v[116:117], off offset:16
	s_waitcnt vmcnt(14)
	v_lshlrev_b32_e32 v12, 16, v54
	s_waitcnt vmcnt(13)
	v_cndmask_b32_e64 v78, v78, 0, s[40:41]
	v_lshlrev_b32_e32 v164, 16, v50
	v_cndmask_b32_e32 v12, v12, v78, vcc
	v_sub_f32_e32 v12, v12, v164
	s_waitcnt vmcnt(12)
	v_fmac_f32_e32 v164, v12, v74
	v_and_b32_e32 v165, 0xffff0000, v50
	v_and_b32_e32 v12, 0xffff0000, v54
	v_cndmask_b32_e64 v50, v79, 0, s[40:41]
	v_cndmask_b32_e32 v12, v12, v50, vcc
	v_sub_f32_e32 v12, v12, v165
	v_fmac_f32_e32 v165, v12, v75
	v_lshlrev_b32_e32 v12, 16, v55
	v_cndmask_b32_e64 v50, v80, 0, s[40:41]
	v_lshlrev_b32_e32 v166, 16, v51
	v_cndmask_b32_e32 v12, v12, v50, vcc
	v_sub_f32_e32 v12, v12, v166
	v_fmac_f32_e32 v166, v12, v76
	v_and_b32_e32 v12, 0xffff0000, v55
	v_cndmask_b32_e64 v50, v81, 0, s[40:41]
	v_and_b32_e32 v169, 0xffff0000, v51
	v_cndmask_b32_e32 v12, v12, v50, vcc
	v_sub_f32_e32 v12, v12, v169
	v_fmac_f32_e32 v169, v12, v77
	v_lshlrev_b32_e32 v12, 16, v56
	s_waitcnt vmcnt(11)
	v_cndmask_b32_e64 v50, v118, 0, s[40:41]
	v_lshlrev_b32_e32 v167, 16, v52
	v_cndmask_b32_e32 v12, v12, v50, vcc
	v_sub_f32_e32 v12, v12, v167
	s_waitcnt vmcnt(10)
; __device__ __forceinline__ float lo2f(unsigned u) { return __uint_as_float(u << 16); }
; __device__ __forceinline__ float hi2f(unsigned u) { return __uint_as_float(u & 0xffff0000u); }
; __device__ __forceinline__ void rwkv_prep_task(KP p, int l, int tile, int hg, bf16_t* sAp) {
;     ...
;     float x3[3][16];
; #pragma unroll
;     for (int q = 0; q < 3; ++q) {
;         const int col = q * 512 + cb;
;         const u32x4 c0 = *(const u32x4*)(P + (size_t)R * PW + col), c1 = *(const u32x4*)(P + (size_t)R * PW + col + 8);
;         const u32x4 p0 = *(const u32x4*)(P + (size_t)(R > 0 ? R - 1 : 0) * PW + col), p1 = *(const u32x4*)(P + (size_t)(R > 0 ? R - 1 : 0) * PW + col + 8);
; #pragma unroll
;         for (int e4 = 0; e4 < 4; ++e4) {
;             const float4 su = *(const float4*)(shs + (size_t)sb * 1792 + col + e4 * 4);
;             const float4 m4 = *(const float4*)(mu + col + e4 * 4);
;             const float sv[4] = {su.x, su.y, su.z, su.w}, mm[4] = {m4.x, m4.y, m4.z, m4.w};
; #pragma unroll
;             for (int k = 0; k < 4; ++k) {
;                 const int e = e4 * 4 + k;
;                 const unsigned cu = e < 8 ? c0[e >> 1] : c1[(e - 8) >> 1], pu = e < 8 ? p0[e >> 1] : p1[(e - 8) >> 1];
;                 const float cv = (e & 1) ? hi2f(cu) : lo2f(cu), pp = (e & 1) ? hi2f(pu) : lo2f(pu);
;                 const float prev = first ? (samp ? sv[k] : 0.f) : pp;
;                 x3[q][e] = cv + (prev - cv) * mm[k];
;             }
;         }
;     }
;     float wd[16], kp[16], kkv[16], av[16], gv[16];
;     float ss = 0.f, bon = 0.f;
; #pragma unroll
;     for (int e4 = 0; e4 < 4; ++e4) {
;         const float4 w04 = *(const float4*)(p->in[I_W0] + l * 512 + cb + e4 * 4), a04 = *(const float4*)(p->in[I_A0] + l * 512 + cb + e4 * 4);
;         const float4 kk4 = *(const float4*)(p->in[I_KK] + l * 512 + cb + e4 * 4), ka4 = *(const float4*)(p->in[I_KA] + l * 512 + cb + e4 * 4);
;         const float4 rk4 = *(const float4*)(p->in[I_RK] + l * 512 + cb + e4 * 4);
	v_fmac_f32_e32 v167, v12, v122
	v_and_b32_e32 v12, 0xffff0000, v56
	v_cndmask_b32_e64 v50, v119, 0, s[40:41]
	v_and_b32_e32 v170, 0xffff0000, v52
	v_cndmask_b32_e32 v12, v12, v50, vcc
	v_sub_f32_e32 v12, v12, v170
	v_lshlrev_b32_e32 v50, 16, v57
	v_cndmask_b32_e64 v51, v120, 0, s[40:41]
	v_fmac_f32_e32 v170, v12, v123
	v_lshlrev_b32_e32 v12, 16, v53
	v_cndmask_b32_e32 v50, v50, v51, vcc
	v_sub_f32_e32 v50, v50, v12
	v_fmac_f32_e32 v12, v50, v124
	v_and_b32_e32 v50, 0xffff0000, v57
	v_cndmask_b32_e64 v51, v121, 0, s[40:41]
	v_and_b32_e32 v163, 0xffff0000, v53
	v_cndmask_b32_e32 v50, v50, v51, vcc
	v_sub_f32_e32 v50, v50, v163
	v_fmac_f32_e32 v163, v50, v125
	global_load_dwordx4 v[50:53], v[88:89], off offset:1040
	global_load_dwordx4 v[94:97], v[88:89], off offset:1024
	global_load_dwordx4 v[54:57], v[90:91], off offset:1040
	s_nop 0
	global_load_dwordx4 v[90:93], v[90:91], off offset:1024
	s_nop 0
	global_load_dwordx4 v[74:77], v[114:115], off offset:48
	s_nop 0
	global_load_dwordx4 v[114:117], v[116:117], off offset:48
	s_waitcnt vmcnt(14)
	v_lshlrev_b32_e32 v178, 16, v66
	s_waitcnt vmcnt(12)
	v_lshlrev_b32_e32 v78, 16, v70
	v_and_b32_e32 v179, 0xffff0000, v66
	v_and_b32_e32 v66, 0xffff0000, v70
	s_waitcnt vmcnt(11)
	v_cndmask_b32_e64 v70, v127, 0, s[40:41]
	v_cndmask_b32_e32 v66, v66, v70, vcc
	v_sub_f32_e32 v66, v66, v179
	s_waitcnt vmcnt(10)
	v_fmac_f32_e32 v179, v66, v131
	v_lshlrev_b32_e32 v66, 16, v71
	v_cndmask_b32_e64 v70, v128, 0, s[40:41]
	v_lshlrev_b32_e32 v180, 16, v67
	v_cndmask_b32_e32 v66, v66, v70, vcc
	v_sub_f32_e32 v66, v66, v180
	v_fmac_f32_e32 v180, v66, v132
	v_and_b32_e32 v182, 0xffff0000, v67
	v_and_b32_e32 v66, 0xffff0000, v71
	v_cndmask_b32_e64 v67, v129, 0, s[40:41]
	v_cndmask_b32_e32 v66, v66, v67, vcc
	v_sub_f32_e32 v66, v66, v182
	s_load_dwordx2 s[12:13], s[16:17], 0x60
	s_load_dwordx2 s[18:19], s[16:17], 0x70
	v_fmac_f32_e32 v182, v66, v133
	v_lshlrev_b32_e32 v66, 16, v72
	s_waitcnt vmcnt(8)
	v_cndmask_b32_e64 v67, v102, 0, s[40:41]
	v_lshlrev_b32_e32 v184, 16, v68
	v_cndmask_b32_e32 v66, v66, v67, vcc
	v_sub_f32_e32 v66, v66, v184
	v_cndmask_b32_e64 v67, v103, 0, s[40:41]
	v_cndmask_b32_e64 v79, v126, 0, s[40:41]
	v_and_b32_e32 v185, 0xffff0000, v68
	s_waitcnt vmcnt(6)
	v_fmac_f32_e32 v184, v66, v110
	v_and_b32_e32 v66, 0xffff0000, v72
	v_cndmask_b32_e32 v66, v66, v67, vcc
	s_waitcnt lgkmcnt(0)
	s_add_u32 s12, s12, s14
	v_cndmask_b32_e32 v78, v78, v79, vcc
	v_sub_f32_e32 v66, v66, v185
	s_addc_u32 s13, s13, s15
	v_sub_f32_e32 v78, v78, v178
	v_fmac_f32_e32 v185, v66, v111
	v_lshl_add_u64 v[66:67], s[12:13], 0, v[86:87]
	v_fmac_f32_e32 v178, v78, v130
	global_load_dwordx4 v[78:81], v[66:67], off offset:16
	global_load_dwordx4 v[142:145], v[66:67], off
	v_lshlrev_b32_e32 v68, 16, v73
	v_cndmask_b32_e64 v70, v104, 0, s[40:41]
	v_lshlrev_b32_e32 v187, 16, v69
	v_cndmask_b32_e32 v68, v68, v70, vcc
	v_sub_f32_e32 v68, v68, v187
	v_fmac_f32_e32 v187, v68, v112
	v_and_b32_e32 v210, 0xffff0000, v69
	v_and_b32_e32 v68, 0xffff0000, v73
	v_cndmask_b32_e64 v69, v105, 0, s[40:41]
	v_cndmask_b32_e32 v68, v68, v69, vcc
	v_sub_f32_e32 v68, v68, v210
	v_fmac_f32_e32 v210, v68, v113
	v_lshlrev_b32_e32 v186, 16, v58
	v_lshlrev_b32_e32 v68, 16, v62
	v_and_b32_e32 v188, 0xffff0000, v58
	v_and_b32_e32 v58, 0xffff0000, v62
	v_cndmask_b32_e64 v62, v99, 0, s[40:41]
	v_cndmask_b32_e32 v58, v58, v62, vcc
	v_sub_f32_e32 v58, v58, v188
	v_fmac_f32_e32 v188, v58, v107
	v_lshlrev_b32_e32 v58, 16, v63
	v_cndmask_b32_e64 v62, v100, 0, s[40:41]
	v_lshlrev_b32_e32 v189, 16, v59
	v_cndmask_b32_e32 v58, v58, v62, vcc
	s_add_u32 s12, s18, s14
	v_sub_f32_e32 v58, v58, v189
	s_addc_u32 s13, s19, s15
	v_fmac_f32_e32 v189, v58, v108
	v_and_b32_e32 v190, 0xffff0000, v59
	v_lshl_add_u64 v[58:59], s[12:13], 0, v[86:87]
	global_load_dwordx4 v[118:121], v[58:59], off offset:16
	global_load_dwordx4 v[146:149], v[58:59], off
	s_load_dwordx4 s[76:79], s[16:17], 0x88
	s_load_dwordx2 s[12:13], s[16:17], 0x98
	global_load_dwordx4 v[134:137], v[82:83], off offset:2064
	global_load_dwordx4 v[212:215], v[82:83], off offset:2048
	v_and_b32_e32 v62, 0xffff0000, v63
	v_cndmask_b32_e64 v63, v101, 0, s[40:41]
	v_cndmask_b32_e32 v62, v62, v63, vcc
	v_sub_f32_e32 v62, v62, v190
	v_fmac_f32_e32 v190, v62, v109
	v_lshlrev_b32_e32 v62, 16, v64
	s_waitcnt vmcnt(7)
	v_cndmask_b32_e64 v63, v74, 0, s[40:41]
	v_lshlrev_b32_e32 v191, 16, v60
	v_cndmask_b32_e32 v62, v62, v63, vcc
	v_sub_f32_e32 v62, v62, v191
	s_waitcnt vmcnt(6)
	v_fmac_f32_e32 v191, v62, v114
	v_and_b32_e32 v209, 0xffff0000, v60
	v_and_b32_e32 v60, 0xffff0000, v64
	v_cndmask_b32_e64 v62, v75, 0, s[40:41]
	v_cndmask_b32_e32 v60, v60, v62, vcc
	v_sub_f32_e32 v60, v60, v209
	v_fmac_f32_e32 v209, v60, v115
	v_lshlrev_b32_e32 v60, 16, v65
	v_cndmask_b32_e64 v62, v76, 0, s[40:41]
	s_waitcnt lgkmcnt(0)
	s_add_u32 s18, s76, s14
	v_lshlrev_b32_e32 v181, 16, v61
	v_cndmask_b32_e32 v60, v60, v62, vcc
	s_addc_u32 s19, s77, s15
	v_sub_f32_e32 v60, v60, v181
	v_lshl_add_u64 v[158:159], s[18:19], 0, v[86:87]
	s_add_u32 s18, s78, s14
	v_fmac_f32_e32 v181, v60, v116
	v_and_b32_e32 v183, 0xffff0000, v61
	v_and_b32_e32 v60, 0xffff0000, v65
	v_cndmask_b32_e64 v61, v77, 0, s[40:41]
	s_addc_u32 s19, s79, s15
	global_load_dwordx4 v[126:129], v[84:85], off offset:2064
	global_load_dwordx4 v[216:219], v[84:85], off offset:2048
	v_cndmask_b32_e32 v60, v60, v61, vcc
	s_add_u32 s12, s12, s14
	v_sub_f32_e32 v60, v60, v183
	s_addc_u32 s13, s13, s15
	v_fmac_f32_e32 v183, v60, v117
	v_lshl_add_u64 v[60:61], s[18:19], 0, v[86:87]
	v_lshl_add_u64 v[70:71], s[12:13], 0, v[86:87]
	global_load_dwordx4 v[220:223], v[60:61], off
	global_load_dwordx4 v[86:89], v[66:67], off offset:48
	global_load_dwordx4 v[110:113], v[66:67], off offset:32
	global_load_dwordx4 v[138:141], v[60:61], off offset:16
	global_load_dwordx4 v[130:133], v[70:71], off offset:16
	global_load_dwordx4 v[224:227], v[70:71], off
	v_cndmask_b32_e64 v69, v98, 0, s[40:41]
	v_cndmask_b32_e32 v68, v68, v69, vcc
	v_sub_f32_e32 v68, v68, v186
	v_fmac_f32_e32 v186, v68, v106
	s_waitcnt vmcnt(12)
; __device__ __forceinline__ float sigmoid_(float x) { return __builtin_amdgcn_rcpf(1.f + __expf(-x)); }
; __device__ __forceinline__ float softplus_(float x) { return fmaxf(x, 0.f) + __logf(1.f + __expf(-fabsf(x))); }
; __device__ __forceinline__ void rwkv_prep_task(KP p, int l, int tile, int hg, bf16_t* sAp) {
;     ...
; #pragma unroll
;     for (int e4 = 0; e4 < 4; ++e4) {
;         const float4 w04 = *(const float4*)(p->in[I_W0] + l * 512 + cb + e4 * 4), a04 = *(const float4*)(p->in[I_A0] + l * 512 + cb + e4 * 4);
;         const float4 kk4 = *(const float4*)(p->in[I_KK] + l * 512 + cb + e4 * 4), ka4 = *(const float4*)(p->in[I_KA] + l * 512 + cb + e4 * 4);
;         const float4 rk4 = *(const float4*)(p->in[I_RK] + l * 512 + cb + e4 * 4);
;         const float w0v[4] = {w04.x, w04.y, w04.z, w04.w}, a0v[4] = {a04.x, a04.y, a04.z, a04.w};
;         const float kkp[4] = {kk4.x, kk4.y, kk4.z, kk4.w}, kap[4] = {ka4.x, ka4.y, ka4.z, ka4.w}, rkp[4] = {rk4.x, rk4.y, rk4.z, rk4.w};
; #pragma unroll
;         for (int k = 0; k < 4; ++k) {
;             const int e = e4 * 4 + k;
;             const float z = w0v[k] + az[k][e4];
;             wd[e] = __expf(-__expf(-softplus_(-z) - 0.5f));
;             const float a = sigmoid_(a0v[k] + aa[k][e4]);
;             const float kx = x3[1][e];
;             kkv[e] = kx * kkp[k];
;             kp[e] = kx * (1.f + (a - 1.f) * kap[k]);
;             av[e] = a; gv[e] = ag[k][e4];
;             ss += kkv[e] * kkv[e];
;             bon += x3[0][e] * kp[e] * rkp[k];
;         }
	v_add_f32_e32 v14, v14, v142
	v_mul_f32_e64 v62, |v14|, s28
	v_exp_f32_e32 v62, v62
	v_max_f32_e64 v14, -v14, 0
	v_add_f32_e32 v22, v22, v143
	v_add_f32_e32 v62, 1.0, v62
	v_cmp_gt_f32_e64 s[42:43], s63, v62
	s_waitcnt vmcnt(11)
	v_add_f32_e32 v9, v9, v118
	v_cndmask_b32_e64 v63, 0, 32, s[42:43]
	v_ldexp_f32 v62, v62, v63
	v_log_f32_e32 v62, v62
	s_waitcnt vmcnt(10)
	v_add_f32_e32 v8, v8, v146
	v_mul_f32_e32 v8, 0xbfb8aa3b, v8
	v_exp_f32_e32 v8, v8
	v_mul_f32_e32 v63, 0x3f317217, v62
	v_fma_f32 v63, v62, s67, -v63
	v_fmac_f32_e32 v63, 0x3377d1cf, v62
	v_fmac_f32_e32 v63, 0x3f317217, v62
	v_cmp_lt_f32_e64 s[44:45], |v62|, s2
	v_add_f32_e32 v18, v18, v147
	v_mul_f32_e32 v18, 0xbfb8aa3b, v18
	v_cndmask_b32_e64 v62, v62, v63, s[44:45]
	v_cndmask_b32_e64 v63, 0, v203, s[42:43]
	v_sub_f32_e32 v62, v62, v63
	v_add_f32_e32 v14, v14, v62
	global_load_dwordx4 v[66:69], v[58:59], off offset:48
	global_load_dwordx4 v[102:105], v[58:59], off offset:32
	global_load_dwordx4 v[62:65], v[70:71], off offset:48
	global_load_dwordx4 v[98:101], v[70:71], off offset:32
	v_mul_f32_e64 v58, |v22|, s28
	v_exp_f32_e32 v58, v58
	v_sub_f32_e32 v14, -0.5, v14
	v_mul_f32_e32 v14, 0x3fb8aa3b, v14
	v_exp_f32_e32 v14, v14
	v_add_f32_e32 v58, 1.0, v58
	v_cmp_gt_f32_e64 s[42:43], s63, v58
	v_exp_f32_e32 v18, v18
	v_mul_f32_e32 v14, 0xbfb8aa3b, v14
	v_cndmask_b32_e64 v59, 0, 32, s[42:43]
	v_ldexp_f32 v58, v58, v59
	v_log_f32_e32 v59, v58
	v_exp_f32_e32 v58, v14
	v_max_f32_e64 v14, -v22, 0
	v_add_f32_e32 v8, 1.0, v8
	v_mul_f32_e32 v22, 0x3f317217, v59
	v_fma_f32 v22, v59, s67, -v22
	v_fmac_f32_e32 v22, 0x3377d1cf, v59
	v_fmac_f32_e32 v22, 0x3f317217, v59
	v_cmp_lt_f32_e64 s[44:45], |v59|, s2
	v_rcp_f32_e32 v142, v8
	global_load_dwordx4 v[74:77], v[82:83], off offset:2096
	global_load_dwordx4 v[114:117], v[82:83], off offset:2080
	global_load_dwordx4 v[70:73], v[84:85], off offset:2096
	global_load_dwordx4 v[106:109], v[84:85], off offset:2080
	v_cndmask_b32_e64 v22, v59, v22, s[44:45]
	v_cndmask_b32_e64 v59, 0, v203, s[42:43]
	v_sub_f32_e32 v22, v22, v59
	v_add_f32_e32 v14, v14, v22
	v_sub_f32_e32 v14, -0.5, v14
	v_mul_f32_e32 v14, 0x3fb8aa3b, v14
	v_exp_f32_e32 v14, v14
	s_waitcnt vmcnt(16)
	v_cndmask_b32_e64 v22, v213, 0, s[40:41]
	v_lshlrev_b32_e32 v82, 16, v94
	v_and_b32_e32 v83, 0xffff0000, v94
	v_mul_f32_e32 v8, 0xbfb8aa3b, v14
	v_exp_f32_e32 v59, v8
	v_add_f32_e32 v8, 1.0, v18
	v_rcp_f32_e32 v143, v8
	v_lshlrev_b32_e32 v8, 16, v90
	v_cndmask_b32_e64 v18, v212, 0, s[40:41]
	v_and_b32_e32 v14, 0xffff0000, v90
	v_cndmask_b32_e32 v84, v8, v18, vcc
	v_add_f32_e32 v8, v34, v144
	v_cndmask_b32_e32 v85, v14, v22, vcc
	v_mul_f32_e64 v14, |v8|, s28
	v_exp_f32_e32 v14, v14
	v_pk_add_f32 v[84:85], v[84:85], v[82:83] neg_lo:[0,1] neg_hi:[0,1]
	v_max_f32_e64 v8, -v8, 0
	s_waitcnt vmcnt(14)
	v_pk_fma_f32 v[146:147], v[84:85], v[216:217], v[82:83]
	v_add_f32_e32 v14, 1.0, v14
	v_cmp_gt_f32_e64 s[42:43], s63, v14
	v_pk_add_f32 v[82:83], v[142:143], -1.0 op_sel_hi:[1,0]
	v_lshlrev_b32_e32 v94, 16, v95
	v_cndmask_b32_e64 v18, 0, 32, s[42:43]
	v_ldexp_f32 v14, v14, v18
	v_log_f32_e32 v14, v14
	s_waitcnt vmcnt(13)
	v_pk_fma_f32 v[82:83], v[82:83], v[220:221], 1.0 op_sel_hi:[1,1,0]
	v_and_b32_e32 v95, 0xffff0000, v95
	v_pk_mul_f32 v[160:161], v[146:147], v[82:83]
	v_mul_f32_e32 v22, 0x3f317217, v14
	v_fma_f32 v22, v14, s67, -v22
	v_fmac_f32_e32 v22, 0x3377d1cf, v14
	v_fmac_f32_e32 v22, 0x3f317217, v14
	v_cmp_lt_f32_e64 s[44:45], |v14|, s2
	v_mul_f32_e32 v18, v172, v160
	s_waitcnt vmcnt(8)
	v_fma_f32 v211, v224, v18, 0
	v_cndmask_b32_e64 v14, v14, v22, s[44:45]
	v_cndmask_b32_e64 v22, 0, v203, s[42:43]
	v_sub_f32_e32 v14, v14, v22
	v_add_f32_e32 v8, v8, v14
	v_mul_f32_e32 v14, v174, v161
	v_fmac_f32_e32 v211, v225, v14
	v_add_f32_e32 v14, v46, v145
	v_mul_f32_e64 v18, |v14|, s28
	v_exp_f32_e32 v18, v18
	v_sub_f32_e32 v8, -0.5, v8
	v_mul_f32_e32 v8, 0x3fb8aa3b, v8
	v_add_f32_e32 v22, v30, v148
	v_add_f32_e32 v18, 1.0, v18
	v_cmp_gt_f32_e64 s[42:43], s63, v18
	v_exp_f32_e32 v8, v8
	v_mul_f32_e32 v22, 0xbfb8aa3b, v22
	v_cndmask_b32_e64 v30, 0, 32, s[42:43]
	v_ldexp_f32 v18, v18, v30
	v_exp_f32_e32 v22, v22
	v_log_f32_e32 v18, v18
	v_mul_f32_e32 v8, 0xbfb8aa3b, v8
	global_load_dwordx4 v[82:85], v[60:61], off offset:48
	global_load_dwordx4 v[122:125], v[60:61], off offset:32
	v_exp_f32_e32 v60, v8
	v_add_f32_e32 v8, 1.0, v22
	v_mul_f32_e32 v22, 0x3f317217, v18
	v_fma_f32 v22, v18, s67, -v22
	v_fmac_f32_e32 v22, 0x3377d1cf, v18
	v_fmac_f32_e32 v22, 0x3f317217, v18
	v_cmp_lt_f32_e64 s[44:45], |v18|, s2
	v_max_f32_e64 v14, -v14, 0
	v_rcp_f32_e32 v144, v8
	v_cndmask_b32_e64 v18, v18, v22, s[44:45]
	v_cndmask_b32_e64 v22, 0, v203, s[42:43]
	v_sub_f32_e32 v18, v18, v22
	v_add_f32_e32 v14, v14, v18
	v_sub_f32_e32 v14, -0.5, v14
	v_mul_f32_e32 v14, 0x3fb8aa3b, v14
	v_add_f32_e32 v18, v42, v149
	v_exp_f32_e32 v14, v14
	v_mul_f32_e32 v18, 0xbfb8aa3b, v18
	v_exp_f32_e32 v18, v18
	v_cndmask_b32_e64 v22, v215, 0, s[40:41]
	v_mul_f32_e32 v8, 0xbfb8aa3b, v14
	v_exp_f32_e32 v61, v8
	v_add_f32_e32 v8, 1.0, v18
	v_rcp_f32_e32 v145, v8
	v_lshlrev_b32_e32 v8, 16, v91
	v_cndmask_b32_e64 v18, v214, 0, s[40:41]
	v_and_b32_e32 v14, 0xffff0000, v91
	v_cndmask_b32_e32 v90, v8, v18, vcc
	v_add_f32_e32 v8, v15, v78
	v_cndmask_b32_e32 v91, v14, v22, vcc
	v_mul_f32_e64 v14, |v8|, s28
	v_exp_f32_e32 v18, v14
	v_pk_add_f32 v[90:91], v[90:91], v[94:95] neg_lo:[0,1] neg_hi:[0,1]
	v_pk_add_f32 v[14:15], v[144:145], -1.0 op_sel_hi:[1,0]
	v_pk_fma_f32 v[94:95], v[90:91], v[218:219], v[94:95]
	v_add_f32_e32 v18, 1.0, v18
	v_cmp_gt_f32_e64 s[42:43], s63, v18
	v_pk_fma_f32 v[14:15], v[14:15], v[222:223], 1.0 op_sel_hi:[1,1,0]
; __device__ __forceinline__ float sigmoid_(float x) { return __builtin_amdgcn_rcpf(1.f + __expf(-x)); }
; __device__ __forceinline__ float softplus_(float x) { return fmaxf(x, 0.f) + __logf(1.f + __expf(-fabsf(x))); }
; __device__ __forceinline__ void rwkv_prep_task(KP p, int l, int tile, int hg, bf16_t* sAp) {
;     ...
; #pragma unroll
;     for (int e4 = 0; e4 < 4; ++e4) {
;         const float4 w04 = *(const float4*)(p->in[I_W0] + l * 512 + cb + e4 * 4), a04 = *(const float4*)(p->in[I_A0] + l * 512 + cb + e4 * 4);
;         const float4 kk4 = *(const float4*)(p->in[I_KK] + l * 512 + cb + e4 * 4), ka4 = *(const float4*)(p->in[I_KA] + l * 512 + cb + e4 * 4);
;         const float4 rk4 = *(const float4*)(p->in[I_RK] + l * 512 + cb + e4 * 4);
;         const float w0v[4] = {w04.x, w04.y, w04.z, w04.w}, a0v[4] = {a04.x, a04.y, a04.z, a04.w};
;         const float kkp[4] = {kk4.x, kk4.y, kk4.z, kk4.w}, kap[4] = {ka4.x, ka4.y, ka4.z, ka4.w}, rkp[4] = {rk4.x, rk4.y, rk4.z, rk4.w};
; #pragma unroll
;         for (int k = 0; k < 4; ++k) {
;             const int e = e4 * 4 + k;
;             const float z = w0v[k] + az[k][e4];
;             wd[e] = __expf(-__expf(-softplus_(-z) - 0.5f));
;             const float a = sigmoid_(a0v[k] + aa[k][e4]);
;             const float kx = x3[1][e];
;             kkv[e] = kx * kkp[k];
;             kp[e] = kx * (1.f + (a - 1.f) * kap[k]);
;             av[e] = a; gv[e] = ag[k][e4];
;             ss += kkv[e] * kkv[e];
;             bon += x3[0][e] * kp[e] * rkp[k];
;         }
	v_max_f32_e64 v8, -v8, 0
	v_cndmask_b32_e64 v22, 0, 32, s[42:43]
	v_ldexp_f32 v18, v18, v22
	v_log_f32_e32 v18, v18
	v_pk_mul_f32 v[148:149], v[94:95], v[14:15]
	v_mul_f32_e32 v9, 0xbfb8aa3b, v9
	v_mul_f32_e32 v14, v173, v148
	v_mul_f32_e32 v15, 0x3f317217, v18
	v_fma_f32 v15, v18, s67, -v15
	v_fmac_f32_e32 v15, 0x3377d1cf, v18
	v_fmac_f32_e32 v15, 0x3f317217, v18
	v_cmp_lt_f32_e64 s[44:45], |v18|, s2
	v_fmac_f32_e32 v211, v226, v14
	v_mul_f32_e32 v14, v176, v149
	v_cndmask_b32_e64 v15, v18, v15, s[44:45]
	v_cndmask_b32_e64 v18, 0, v203, s[42:43]
	v_sub_f32_e32 v15, v15, v18
	v_fmac_f32_e32 v211, v227, v14
	v_add_f32_e32 v14, v23, v79
	v_add_f32_e32 v8, v8, v15
	v_mul_f32_e64 v15, |v14|, s28
	v_exp_f32_e32 v15, v15
	v_sub_f32_e32 v8, -0.5, v8
	v_mul_f32_e32 v8, 0x3fb8aa3b, v8
	v_exp_f32_e32 v8, v8
	v_add_f32_e32 v15, 1.0, v15
	v_cmp_gt_f32_e64 s[42:43], s63, v15
	v_exp_f32_e32 v9, v9
	v_mul_f32_e32 v8, 0xbfb8aa3b, v8
	v_cndmask_b32_e64 v18, 0, 32, s[42:43]
	v_ldexp_f32 v15, v15, v18
	v_log_f32_e32 v15, v15
	v_exp_f32_e32 v78, v8
	v_add_f32_e32 v8, 1.0, v9
	v_max_f32_e64 v9, -v14, 0
	v_mul_f32_e32 v14, 0x3f317217, v15
	v_fma_f32 v14, v15, s67, -v14
	v_fmac_f32_e32 v14, 0x3377d1cf, v15
	v_fmac_f32_e32 v14, 0x3f317217, v15
	v_cmp_lt_f32_e64 s[44:45], |v15|, s2
	v_lshlrev_b32_e32 v18, 16, v92
	v_cndmask_b32_e64 v22, v134, 0, s[40:41]
	v_cndmask_b32_e64 v14, v15, v14, s[44:45]
	v_cndmask_b32_e64 v15, 0, v203, s[42:43]
	v_sub_f32_e32 v14, v14, v15
	v_add_f32_e32 v9, v9, v14
	v_sub_f32_e32 v9, -0.5, v9
	v_mul_f32_e32 v9, 0x3fb8aa3b, v9
	v_add_f32_e32 v14, v19, v119
	v_exp_f32_e32 v9, v9
	v_mul_f32_e32 v14, 0xbfb8aa3b, v14
	v_exp_f32_e32 v15, v14
	v_add_f32_e32 v30, v35, v80
	v_cndmask_b32_e32 v18, v18, v22, vcc
	v_mul_f32_e64 v22, |v30|, s28
	v_rcp_f32_e32 v14, v8
	v_mul_f32_e32 v8, 0xbfb8aa3b, v9
	v_exp_f32_e32 v34, v22
	v_exp_f32_e32 v79, v8
	v_add_f32_e32 v8, 1.0, v15
	v_and_b32_e32 v19, 0xffff0000, v92
	v_cndmask_b32_e64 v23, v135, 0, s[40:41]
	v_rcp_f32_e32 v15, v8
	v_lshlrev_b32_e32 v8, 16, v96
	v_and_b32_e32 v9, 0xffff0000, v96
	v_cndmask_b32_e32 v19, v19, v23, vcc
	v_pk_add_f32 v[18:19], v[18:19], v[8:9] neg_lo:[0,1] neg_hi:[0,1]
	v_cndmask_b32_e64 v42, v136, 0, s[40:41]
	v_pk_fma_f32 v[22:23], v[18:19], v[126:127], v[8:9]
	v_add_f32_e32 v18, 1.0, v34
	v_cmp_gt_f32_e64 s[42:43], s63, v18
	v_pk_add_f32 v[8:9], v[14:15], -1.0 op_sel_hi:[1,0]
	v_add_f32_e32 v16, v16, v110
	v_cndmask_b32_e64 v19, 0, 32, s[42:43]
	v_ldexp_f32 v18, v18, v19
	v_log_f32_e32 v18, v18
	v_pk_fma_f32 v[8:9], v[8:9], v[138:139], 1.0 op_sel_hi:[1,1,0]
	s_waitcnt vmcnt(8)
	v_add_f32_e32 v10, v10, v102
	v_pk_mul_f32 v[34:35], v[22:23], v[8:9]
	v_mul_f32_e32 v19, 0x3f317217, v18
	v_fma_f32 v19, v18, s67, -v19
	v_fmac_f32_e32 v19, 0x3377d1cf, v18
	v_fmac_f32_e32 v19, 0x3f317217, v18
	v_cmp_lt_f32_e64 s[44:45], |v18|, s2
	v_max_f32_e64 v9, -v30, 0
	v_mul_f32_e32 v8, v175, v34
	v_cndmask_b32_e64 v18, v18, v19, s[44:45]
	v_cndmask_b32_e64 v19, 0, v203, s[42:43]
	v_sub_f32_e32 v18, v18, v19
	v_add_f32_e32 v9, v9, v18
	v_sub_f32_e32 v9, -0.5, v9
	v_mul_f32_e32 v9, 0x3fb8aa3b, v9
	v_exp_f32_e32 v9, v9
	v_fmac_f32_e32 v211, v130, v8
	v_mul_f32_e32 v8, v177, v35
	v_fmac_f32_e32 v211, v131, v8
	v_mul_f32_e32 v8, 0xbfb8aa3b, v9
	v_add_f32_e32 v9, v47, v81
	v_mul_f32_e64 v18, |v9|, s28
	v_exp_f32_e32 v18, v18
	v_add_f32_e32 v19, v31, v120
	v_mul_f32_e32 v19, 0xbfb8aa3b, v19
	v_exp_f32_e32 v19, v19
	v_add_f32_e32 v18, 1.0, v18
	v_cmp_gt_f32_e64 s[42:43], s63, v18
	v_exp_f32_e32 v80, v8
	v_add_f32_e32 v8, 1.0, v19
	v_cndmask_b32_e64 v30, 0, 32, s[42:43]
	v_ldexp_f32 v18, v18, v30
	v_log_f32_e32 v18, v18
	v_max_f32_e64 v9, -v9, 0
	v_lshlrev_b32_e32 v30, 16, v93
	v_cndmask_b32_e32 v30, v30, v42, vcc
	v_mul_f32_e32 v19, 0x3f317217, v18
	v_fma_f32 v19, v18, s67, -v19
	v_fmac_f32_e32 v19, 0x3377d1cf, v18
	v_fmac_f32_e32 v19, 0x3f317217, v18
	v_cmp_lt_f32_e64 s[44:45], |v18|, s2
	v_mul_f32_e64 v42, |v16|, s28
	v_exp_f32_e32 v46, v42
	v_cndmask_b32_e64 v18, v18, v19, s[44:45]
	v_cndmask_b32_e64 v19, 0, v203, s[42:43]
	v_sub_f32_e32 v18, v18, v19
	v_add_f32_e32 v9, v9, v18
	v_sub_f32_e32 v9, -0.5, v9
	v_mul_f32_e32 v9, 0x3fb8aa3b, v9
	v_add_f32_e32 v18, v43, v121
	v_exp_f32_e32 v9, v9
	v_mul_f32_e32 v18, 0xbfb8aa3b, v18
	v_exp_f32_e32 v19, v18
	v_rcp_f32_e32 v18, v8
	v_mul_f32_e32 v8, 0xbfb8aa3b, v9
	v_exp_f32_e32 v81, v8
	v_add_f32_e32 v8, 1.0, v19
	v_and_b32_e32 v31, 0xffff0000, v93
	v_cndmask_b32_e64 v43, v137, 0, s[40:41]
	v_rcp_f32_e32 v19, v8
	v_lshlrev_b32_e32 v8, 16, v97
	v_and_b32_e32 v9, 0xffff0000, v97
	v_cndmask_b32_e32 v31, v31, v43, vcc
	v_pk_add_f32 v[30:31], v[30:31], v[8:9] neg_lo:[0,1] neg_hi:[0,1]
	v_mul_f32_e32 v10, 0xbfb8aa3b, v10
	v_pk_fma_f32 v[42:43], v[30:31], v[128:129], v[8:9]
	v_add_f32_e32 v30, 1.0, v46
	v_cmp_gt_f32_e64 s[42:43], s63, v30
	v_pk_add_f32 v[8:9], v[18:19], -1.0 op_sel_hi:[1,0]
	v_exp_f32_e32 v10, v10
	v_cndmask_b32_e64 v31, 0, 32, s[42:43]
	v_ldexp_f32 v30, v30, v31
	v_log_f32_e32 v30, v30
	v_pk_fma_f32 v[8:9], v[8:9], v[140:141], 1.0 op_sel_hi:[1,1,0]
	v_add_f32_e32 v11, v11, v66
	v_pk_mul_f32 v[46:47], v[42:43], v[8:9]
	v_max_f32_e64 v9, -v16, 0
	v_mul_f32_e32 v16, 0x3f317217, v30
	v_fma_f32 v16, v30, s67, -v16
	v_fmac_f32_e32 v16, 0x3377d1cf, v30
	v_fmac_f32_e32 v16, 0x3f317217, v30
	v_cmp_lt_f32_e64 s[44:45], |v30|, s2
	v_mul_f32_e32 v8, v168, v46
	v_fmac_f32_e32 v211, v132, v8
	v_cndmask_b32_e64 v16, v30, v16, s[44:45]
	v_cndmask_b32_e64 v30, 0, v203, s[42:43]
	v_sub_f32_e32 v16, v16, v30
	v_add_f32_e32 v9, v9, v16
	v_sub_f32_e32 v9, -0.5, v9
	v_mul_f32_e32 v9, 0x3fb8aa3b, v9
	v_exp_f32_e32 v9, v9
	v_mul_f32_e32 v8, v171, v47
	v_fmac_f32_e32 v211, v133, v8
	v_mul_f32_e32 v11, 0xbfb8aa3b, v11
	v_mul_f32_e32 v8, 0xbfb8aa3b, v9
	v_add_f32_e32 v9, v24, v111
	v_mul_f32_e64 v16, |v9|, s28
	v_exp_f32_e32 v16, v16
	v_exp_f32_e32 v90, v8
	v_add_f32_e32 v8, 1.0, v10
	v_max_f32_e64 v9, -v9, 0
	v_add_f32_e32 v16, 1.0, v16
	v_cmp_gt_f32_e64 s[42:43], s63, v16
	v_rcp_f32_e32 v30, v8
	v_exp_f32_e32 v11, v11
	v_cndmask_b32_e64 v24, 0, 32, s[42:43]
	v_ldexp_f32 v16, v16, v24
	v_log_f32_e32 v16, v16
	s_waitcnt vmcnt(4)
; __device__ __forceinline__ float sigmoid_(float x) { return __builtin_amdgcn_rcpf(1.f + __expf(-x)); }
; __device__ __forceinline__ float softplus_(float x) { return fmaxf(x, 0.f) + __logf(1.f + __expf(-fabsf(x))); }
; __device__ __forceinline__ void rwkv_prep_task(KP p, int l, int tile, int hg, bf16_t* sAp) {
;     ...
; #pragma unroll
;     for (int e4 = 0; e4 < 4; ++e4) {
;         const float4 w04 = *(const float4*)(p->in[I_W0] + l * 512 + cb + e4 * 4), a04 = *(const float4*)(p->in[I_A0] + l * 512 + cb + e4 * 4);
;         const float4 kk4 = *(const float4*)(p->in[I_KK] + l * 512 + cb + e4 * 4), ka4 = *(const float4*)(p->in[I_KA] + l * 512 + cb + e4 * 4);
;         const float4 rk4 = *(const float4*)(p->in[I_RK] + l * 512 + cb + e4 * 4);
;         const float w0v[4] = {w04.x, w04.y, w04.z, w04.w}, a0v[4] = {a04.x, a04.y, a04.z, a04.w};
;         const float kkp[4] = {kk4.x, kk4.y, kk4.z, kk4.w}, kap[4] = {ka4.x, ka4.y, ka4.z, ka4.w}, rkp[4] = {rk4.x, rk4.y, rk4.z, rk4.w};
; #pragma unroll
;         for (int k = 0; k < 4; ++k) {
;             const int e = e4 * 4 + k;
;             const float z = w0v[k] + az[k][e4];
;             wd[e] = __expf(-__expf(-softplus_(-z) - 0.5f));
;             const float a = sigmoid_(a0v[k] + aa[k][e4]);
;             const float kx = x3[1][e];
;             kkv[e] = kx * kkp[k];
;             kp[e] = kx * (1.f + (a - 1.f) * kap[k]);
;             av[e] = a; gv[e] = ag[k][e4];
;             ss += kkv[e] * kkv[e];
;             bon += x3[0][e] * kp[e] * rkp[k];
;         }
	v_cndmask_b32_e64 v24, v115, 0, s[40:41]
	v_add_f32_e32 v11, 1.0, v11
	v_add_f32_e32 v33, v33, v68
	v_mul_f32_e32 v10, 0x3f317217, v16
	v_fma_f32 v10, v16, s67, -v10
	v_fmac_f32_e32 v10, 0x3377d1cf, v16
	v_fmac_f32_e32 v10, 0x3f317217, v16
	v_cmp_lt_f32_e64 s[44:45], |v16|, s2
	v_mul_f32_e32 v33, 0xbfb8aa3b, v33
	v_exp_f32_e32 v33, v33
	v_cndmask_b32_e64 v10, v16, v10, s[44:45]
	v_cndmask_b32_e64 v16, 0, v203, s[42:43]
	v_sub_f32_e32 v10, v10, v16
	v_add_f32_e32 v9, v9, v10
	v_sub_f32_e32 v9, -0.5, v9
	v_mul_f32_e32 v9, 0x3fb8aa3b, v9
	v_add_f32_e32 v10, v20, v103
	v_exp_f32_e32 v9, v9
	v_mul_f32_e32 v10, 0xbfb8aa3b, v10
	v_exp_f32_e32 v10, v10
	v_cndmask_b32_e64 v20, v114, 0, s[40:41]
	v_mul_f32_e32 v8, 0xbfb8aa3b, v9
	v_exp_f32_e32 v91, v8
	v_add_f32_e32 v8, 1.0, v10
	v_lshlrev_b32_e32 v10, 16, v54
	v_and_b32_e32 v16, 0xffff0000, v54
	v_cndmask_b32_e32 v92, v10, v20, vcc
	v_add_f32_e32 v10, v36, v112
	v_cndmask_b32_e32 v93, v16, v24, vcc
	v_mul_f32_e64 v16, |v10|, s28
	v_exp_f32_e32 v16, v16
	v_rcp_f32_e32 v31, v8
	v_lshlrev_b32_e32 v8, 16, v50
	v_and_b32_e32 v9, 0xffff0000, v50
	v_add_f32_e32 v16, 1.0, v16
	v_cmp_gt_f32_e64 s[42:43], s63, v16
	v_pk_add_f32 v[92:93], v[92:93], v[8:9] neg_lo:[0,1] neg_hi:[0,1]
	v_cndmask_b32_e64 v24, v117, 0, s[40:41]
	v_cndmask_b32_e64 v20, 0, 32, s[42:43]
	v_ldexp_f32 v16, v16, v20
	v_log_f32_e32 v16, v16
	s_waitcnt vmcnt(2)
	v_pk_fma_f32 v[102:103], v[92:93], v[106:107], v[8:9]
	v_pk_add_f32 v[8:9], v[30:31], -1.0 op_sel_hi:[1,0]
	v_add_f32_e32 v33, 1.0, v33
	s_waitcnt vmcnt(0)
	v_pk_fma_f32 v[8:9], v[8:9], v[122:123], 1.0 op_sel_hi:[1,1,0]
	v_cmp_lt_f32_e64 s[44:45], |v16|, s2
	v_pk_mul_f32 v[106:107], v[102:103], v[8:9]
	v_max_f32_e64 v9, -v10, 0
	v_mul_f32_e32 v10, 0x3f317217, v16
	v_fma_f32 v10, v16, s67, -v10
	v_fmac_f32_e32 v10, 0x3377d1cf, v16
	v_fmac_f32_e32 v10, 0x3f317217, v16
	v_cndmask_b32_e64 v10, v16, v10, s[44:45]
	v_cndmask_b32_e64 v16, 0, v203, s[42:43]
	v_sub_f32_e32 v10, v10, v16
	v_add_f32_e32 v9, v9, v10
	v_sub_f32_e32 v9, -0.5, v9
	v_mul_f32_e32 v9, 0x3fb8aa3b, v9
	v_exp_f32_e32 v9, v9
	v_mul_f32_e32 v8, v164, v106
	v_fmac_f32_e32 v211, v98, v8
	v_mul_f32_e32 v8, v165, v107
	v_fmac_f32_e32 v211, v99, v8
	v_mul_f32_e32 v8, 0xbfb8aa3b, v9
	v_add_f32_e32 v9, v48, v113
	v_mul_f32_e64 v10, |v9|, s28
	v_exp_f32_e32 v10, v10
	v_add_f32_e32 v16, v32, v104
	v_mul_f32_e32 v16, 0xbfb8aa3b, v16
	v_exp_f32_e32 v16, v16
	v_add_f32_e32 v10, 1.0, v10
	v_cmp_gt_f32_e64 s[42:43], s63, v10
	v_exp_f32_e32 v92, v8
	v_add_f32_e32 v8, 1.0, v16
	v_cndmask_b32_e64 v20, 0, 32, s[42:43]
	v_ldexp_f32 v10, v10, v20
	v_log_f32_e32 v10, v10
	v_max_f32_e64 v9, -v9, 0
	v_rcp_f32_e32 v96, v8
	v_cndmask_b32_e64 v20, v116, 0, s[40:41]
	v_mul_f32_e32 v16, 0x3f317217, v10
	v_fma_f32 v16, v10, s67, -v16
	v_fmac_f32_e32 v16, 0x3377d1cf, v10
	v_fmac_f32_e32 v16, 0x3f317217, v10
	v_cmp_lt_f32_e64 s[44:45], |v10|, s2
	v_add_f32_e32 v32, v37, v88
	global_load_dwordx4 v[112:115], v[158:159], off offset:32
	v_cndmask_b32_e64 v10, v10, v16, s[44:45]
	v_cndmask_b32_e64 v16, 0, v203, s[42:43]
	v_sub_f32_e32 v10, v10, v16
	v_add_f32_e32 v9, v9, v10
	v_sub_f32_e32 v9, -0.5, v9
	v_mul_f32_e32 v9, 0x3fb8aa3b, v9
	v_add_f32_e32 v10, v44, v105
	v_exp_f32_e32 v9, v9
	v_mul_f32_e32 v10, 0xbfb8aa3b, v10
	v_exp_f32_e32 v10, v10
	v_and_b32_e32 v16, 0xffff0000, v55
	v_mul_f32_e32 v8, 0xbfb8aa3b, v9
	v_exp_f32_e32 v93, v8
	v_add_f32_e32 v8, 1.0, v10
	v_lshlrev_b32_e32 v10, 16, v55
	v_cndmask_b32_e32 v50, v10, v20, vcc
	v_add_f32_e32 v10, v17, v86
	v_rcp_f32_e32 v97, v8
	v_lshlrev_b32_e32 v8, 16, v51
	v_and_b32_e32 v9, 0xffff0000, v51
	v_cndmask_b32_e32 v51, v16, v24, vcc
	v_mul_f32_e64 v16, |v10|, s28
	v_exp_f32_e32 v16, v16
	v_pk_add_f32 v[50:51], v[50:51], v[8:9] neg_lo:[0,1] neg_hi:[0,1]
	v_lshlrev_b32_e32 v20, 16, v56
	v_pk_fma_f32 v[54:55], v[50:51], v[108:109], v[8:9]
	v_add_f32_e32 v16, 1.0, v16
	v_cmp_gt_f32_e64 s[42:43], s63, v16
	v_pk_add_f32 v[8:9], v[96:97], -1.0 op_sel_hi:[1,0]
	v_cndmask_b32_e64 v24, v74, 0, s[40:41]
	v_cndmask_b32_e64 v17, 0, 32, s[42:43]
	v_ldexp_f32 v16, v16, v17
	v_log_f32_e32 v16, v16
	v_pk_fma_f32 v[8:9], v[8:9], v[124:125], 1.0 op_sel_hi:[1,1,0]
	v_cndmask_b32_e32 v20, v20, v24, vcc
	v_pk_mul_f32 v[50:51], v[54:55], v[8:9]
	v_max_f32_e64 v9, -v10, 0
	v_mul_f32_e32 v10, 0x3f317217, v16
	v_fma_f32 v10, v16, s67, -v10
	v_fmac_f32_e32 v10, 0x3377d1cf, v16
	v_fmac_f32_e32 v10, 0x3f317217, v16
	v_cmp_lt_f32_e64 s[44:45], |v16|, s2
	v_mul_f32_e32 v8, v166, v50
	v_fmac_f32_e32 v211, v100, v8
	v_cndmask_b32_e64 v10, v16, v10, s[44:45]
	v_cndmask_b32_e64 v16, 0, v203, s[42:43]
	v_sub_f32_e32 v10, v10, v16
	v_add_f32_e32 v9, v9, v10
	v_sub_f32_e32 v9, -0.5, v9
	v_mul_f32_e32 v9, 0x3fb8aa3b, v9
	v_exp_f32_e32 v9, v9
	v_mul_f32_e32 v8, v169, v51
	v_fmac_f32_e32 v211, v101, v8
	v_mul_f32_e64 v24, |v32|, s28
	v_mul_f32_e32 v8, 0xbfb8aa3b, v9
	v_add_f32_e32 v9, v25, v87
	v_mul_f32_e64 v10, |v9|, s28
	v_exp_f32_e32 v10, v10
	v_max_f32_e64 v9, -v9, 0
	v_exp_f32_e32 v36, v24
	v_cndmask_b32_e64 v25, v75, 0, s[40:41]
	v_add_f32_e32 v10, 1.0, v10
	v_cmp_gt_f32_e64 s[42:43], s63, v10
	global_load_dwordx4 v[98:101], v[158:159], off
	global_load_dwordx4 v[108:111], v[158:159], off offset:48
	v_cndmask_b32_e64 v16, 0, 32, s[42:43]
	v_ldexp_f32 v10, v10, v16
	v_log_f32_e32 v10, v10
	v_rcp_f32_e32 v48, v33
	v_and_b32_e32 v37, 0xffff0000, v57
	v_cndmask_b32_e64 v44, v76, 0, s[40:41]
	v_mul_f32_e32 v16, 0x3f317217, v10
	v_fma_f32 v16, v10, s67, -v16
	v_fmac_f32_e32 v16, 0x3377d1cf, v10
	v_fmac_f32_e32 v16, 0x3f317217, v10
	v_cmp_lt_f32_e64 s[44:45], |v10|, s2
	v_and_b32_e32 v33, 0xffff0000, v53
	v_exp_f32_e32 v8, v8
	v_cndmask_b32_e64 v10, v10, v16, s[44:45]
	v_cndmask_b32_e64 v16, 0, v203, s[42:43]
	v_sub_f32_e32 v10, v10, v16
	v_add_f32_e32 v9, v9, v10
	v_add_f32_e32 v10, v21, v67
	v_mul_f32_e32 v10, 0xbfb8aa3b, v10
	v_exp_f32_e32 v10, v10
	v_and_b32_e32 v21, 0xffff0000, v56
	v_rcp_f32_e32 v16, v11
	v_and_b32_e32 v11, 0xffff0000, v52
	v_add_f32_e32 v10, 1.0, v10
	v_rcp_f32_e32 v17, v10
	v_lshlrev_b32_e32 v10, 16, v52
	v_cndmask_b32_e32 v21, v21, v25, vcc
	v_pk_add_f32 v[20:21], v[20:21], v[10:11] neg_lo:[0,1] neg_hi:[0,1]
	s_waitcnt vmcnt(2)
; __device__ __forceinline__ float sigmoid_(float x) { return __builtin_amdgcn_rcpf(1.f + __expf(-x)); }
; __device__ __forceinline__ float softplus_(float x) { return fmaxf(x, 0.f) + __logf(1.f + __expf(-fabsf(x))); }
; __device__ __forceinline__ void rwkv_prep_task(KP p, int l, int tile, int hg, bf16_t* sAp) {
;     ...
; #pragma unroll
;     for (int e4 = 0; e4 < 4; ++e4) {
;         const float4 w04 = *(const float4*)(p->in[I_W0] + l * 512 + cb + e4 * 4), a04 = *(const float4*)(p->in[I_A0] + l * 512 + cb + e4 * 4);
;         const float4 kk4 = *(const float4*)(p->in[I_KK] + l * 512 + cb + e4 * 4), ka4 = *(const float4*)(p->in[I_KA] + l * 512 + cb + e4 * 4);
;         const float4 rk4 = *(const float4*)(p->in[I_RK] + l * 512 + cb + e4 * 4);
;         const float w0v[4] = {w04.x, w04.y, w04.z, w04.w}, a0v[4] = {a04.x, a04.y, a04.z, a04.w};
;         const float kkp[4] = {kk4.x, kk4.y, kk4.z, kk4.w}, kap[4] = {ka4.x, ka4.y, ka4.z, ka4.w}, rkp[4] = {rk4.x, rk4.y, rk4.z, rk4.w};
; #pragma unroll
;         for (int k = 0; k < 4; ++k) {
;             const int e = e4 * 4 + k;
;             const float z = w0v[k] + az[k][e4];
;             wd[e] = __expf(-__expf(-softplus_(-z) - 0.5f));
;             const float a = sigmoid_(a0v[k] + aa[k][e4]);
;             const float kx = x3[1][e];
;             kkv[e] = kx * kkp[k];
;             kp[e] = kx * (1.f + (a - 1.f) * kap[k]);
;             av[e] = a; gv[e] = ag[k][e4];
;             ss += kkv[e] * kkv[e];
;             bon += x3[0][e] * kp[e] * rkp[k];
;         }
;     }
;     ss += __shfl_xor(ss, 16); ss += __shfl_xor(ss, 32);
;     bon += __shfl_xor(bon, 16); bon += __shfl_xor(bon, 32);
;     const float inv = rsqrtf(ss + 1e-12f);
	v_pk_mul_f32 v[102:103], v[102:103], v[112:113]
	v_pk_fma_f32 v[24:25], v[20:21], v[70:71], v[10:11]
	v_add_f32_e32 v20, 1.0, v36
	v_cmp_gt_f32_e64 s[42:43], s63, v20
	v_pk_add_f32 v[10:11], v[16:17], -1.0 op_sel_hi:[1,0]
	v_pk_mul_f32 v[54:55], v[54:55], v[114:115]
	v_cndmask_b32_e64 v21, 0, 32, s[42:43]
	v_ldexp_f32 v20, v20, v21
	v_log_f32_e32 v36, v20
	v_pk_fma_f32 v[10:11], v[10:11], v[82:83], 1.0 op_sel_hi:[1,1,0]
	v_sub_f32_e32 v9, -0.5, v9
	v_pk_mul_f32 v[20:21], v[24:25], v[10:11]
	v_max_f32_e64 v11, -v32, 0
	v_mul_f32_e32 v32, 0x3f317217, v36
	v_fma_f32 v32, v36, s67, -v32
	v_fmac_f32_e32 v32, 0x3377d1cf, v36
	v_fmac_f32_e32 v32, 0x3f317217, v36
	v_cmp_lt_f32_e64 s[44:45], |v36|, s2
	v_mul_f32_e32 v10, v167, v20
	v_fmac_f32_e32 v211, v62, v10
	v_cndmask_b32_e64 v32, v36, v32, s[44:45]
	v_cndmask_b32_e64 v36, 0, v203, s[42:43]
	v_sub_f32_e32 v32, v32, v36
	v_add_f32_e32 v11, v11, v32
	v_sub_f32_e32 v11, -0.5, v11
	v_mul_f32_e32 v11, 0x3fb8aa3b, v11
	v_exp_f32_e32 v11, v11
	v_mul_f32_e32 v10, v170, v21
	v_fmac_f32_e32 v211, v63, v10
	v_mul_f32_e32 v9, 0x3fb8aa3b, v9
	v_mul_f32_e32 v10, 0xbfb8aa3b, v11
	v_add_f32_e32 v11, v49, v89
	global_load_dwordx4 v[86:89], v[158:159], off offset:16
	v_mul_f32_e64 v32, |v11|, s28
	v_exp_f32_e32 v32, v32
	v_max_f32_e64 v11, -v11, 0
	v_exp_f32_e32 v9, v9
	v_exp_f32_e32 v10, v10
	v_add_f32_e32 v32, 1.0, v32
	v_cmp_gt_f32_e64 s[42:43], s63, v32
	v_mul_f32_e32 v9, 0xbfb8aa3b, v9
	v_exp_f32_e32 v9, v9
	v_cndmask_b32_e64 v36, 0, 32, s[42:43]
	v_ldexp_f32 v32, v32, v36
	v_log_f32_e32 v32, v32
	v_cvt_pk_bf16_f32 v62, v160, v161
	v_cvt_pk_bf16_f32 v66, v172, v174
	v_cvt_pk_bf16_f32 v70, v178, v179
	v_mul_f32_e32 v36, 0x3f317217, v32
	v_fma_f32 v36, v32, s67, -v36
	v_fmac_f32_e32 v36, 0x3377d1cf, v32
	v_fmac_f32_e32 v36, 0x3f317217, v32
	v_cmp_lt_f32_e64 s[44:45], |v32|, s2
	v_cvt_pk_bf16_f32 v63, v148, v149
	v_cvt_pk_bf16_f32 v67, v173, v176
	v_cndmask_b32_e64 v32, v32, v36, s[44:45]
	v_cndmask_b32_e64 v36, 0, v203, s[42:43]
	v_sub_f32_e32 v32, v32, v36
	v_add_f32_e32 v11, v11, v32
	v_add_f32_e32 v32, v45, v69
	v_mul_f32_e32 v32, 0xbfb8aa3b, v32
	v_exp_f32_e32 v32, v32
	v_lshlrev_b32_e32 v36, 16, v57
	v_cndmask_b32_e64 v45, v77, 0, s[40:41]
	v_cndmask_b32_e32 v37, v37, v45, vcc
	v_add_f32_e32 v32, 1.0, v32
	v_rcp_f32_e32 v49, v32
	v_lshlrev_b32_e32 v32, 16, v53
	v_cndmask_b32_e32 v36, v36, v44, vcc
	v_pk_add_f32 v[36:37], v[36:37], v[32:33] neg_lo:[0,1] neg_hi:[0,1]
	v_sub_f32_e32 v11, -0.5, v11
	v_pk_fma_f32 v[44:45], v[36:37], v[72:73], v[32:33]
	v_pk_add_f32 v[32:33], v[48:49], -1.0 op_sel_hi:[1,0]
	v_xor_b32_e32 v36, 32, v193
	v_pk_fma_f32 v[32:33], v[32:33], v[84:85], 1.0 op_sel_hi:[1,1,0]
	v_mul_f32_e32 v11, 0x3fb8aa3b, v11
	v_pk_mul_f32 v[52:53], v[44:45], v[32:33]
	v_and_b32_e32 v33, 64, v193
	v_mul_f32_e32 v32, v12, v52
	v_fmac_f32_e32 v211, v64, v32
	v_mul_f32_e32 v32, v163, v53
	v_fmac_f32_e32 v211, v65, v32
	v_xor_b32_e32 v32, 16, v193
	v_add_u32_e32 v33, 64, v33
	v_cmp_lt_i32_e32 vcc, v32, v33
	v_cvt_pk_bf16_f32 v64, v34, v35
	v_cvt_pk_bf16_f32 v65, v46, v47
	v_cndmask_b32_e32 v32, v193, v32, vcc
	v_cmp_lt_i32_e32 vcc, v36, v33
	s_waitcnt vmcnt(1)
	v_pk_mul_f32 v[46:47], v[44:45], v[110:111]
	v_pk_mul_f32 v[44:45], v[54:55], v[54:55]
	v_cndmask_b32_e32 v33, v193, v36, vcc
	v_lshlrev_b64 v[36:37], 9, v[154:155]
	v_lshl_add_u64 v[36:37], v[36:37], 0, v[156:157]
	v_lshl_add_u64 v[56:57], v[36:37], 2, s[52:53]
	v_lshlrev_b64 v[36:37], 1, v[36:37]
	v_lshl_add_u64 v[74:75], s[54:55], 0, v[36:37]
	v_lshl_add_u64 v[76:77], s[74:75], 0, v[36:37]
	v_lshl_add_u64 v[82:83], s[82:83], 0, v[36:37]
	v_lshl_add_u64 v[84:85], s[84:85], 0, v[36:37]
	v_lshl_add_u64 v[104:105], s[94:95], 0, v[36:37]
	v_lshl_add_u64 v[116:117], s[22:23], 0, v[36:37]
	v_cvt_pk_bf16_f32 v37, v26, v38
	v_cvt_pk_bf16_f32 v38, v1, v5
	v_cvt_pk_bf16_f32 v36, v0, v4
	v_cvt_pk_bf16_f32 v0, v106, v107
	v_pk_mul_f32 v[106:107], v[102:103], v[102:103]
	v_pk_mul_f32 v[26:27], v[46:47], v[46:47]
	v_lshlrev_b32_e32 v118, 2, v32
	v_lshlrev_b32_e32 v119, 2, v33
	v_exp_f32_e32 v11, v11
	ds_bpermute_b32 v32, v118, v211
	s_waitcnt vmcnt(0)
	v_pk_mul_f32 v[34:35], v[42:43], v[88:89]
	v_pk_mul_f32 v[88:89], v[94:95], v[100:101]
	v_pk_mul_f32 v[94:95], v[146:147], v[98:99]
	v_pk_mul_f32 v[42:43], v[88:89], v[88:89]
	v_pk_mul_f32 v[98:99], v[94:95], v[94:95]
	v_pk_mul_f32 v[86:87], v[22:23], v[86:87]
	v_add_f32_e32 v1, v98, v99
	v_add_f32_e32 v1, v1, v42
	v_pk_mul_f32 v[22:23], v[86:87], v[86:87]
	v_add_f32_e32 v1, v1, v43
	v_add_f32_e32 v1, v1, v22
	v_pk_mul_f32 v[4:5], v[34:35], v[34:35]
	v_add_f32_e32 v1, v1, v23
	v_add_f32_e32 v1, v1, v4
	v_add_f32_e32 v1, v1, v5
	v_add_f32_e32 v1, v1, v106
	v_add_f32_e32 v1, v1, v107
	v_pk_mul_f32 v[100:101], v[24:25], v[108:109]
	v_add_f32_e32 v1, v1, v44
	v_pk_mul_f32 v[24:25], v[100:101], v[100:101]
	v_add_f32_e32 v1, v1, v45
	v_add_f32_e32 v1, v1, v24
	v_add_f32_e32 v1, v1, v25
	v_add_f32_e32 v1, v1, v26
	v_add_f32_e32 v5, v1, v27
	ds_bpermute_b32 v23, v118, v5
	v_cvt_pk_bf16_f32 v26, v2, v6
	v_cvt_pk_bf16_f32 v2, v20, v21
	v_mul_f32_e32 v11, 0xbfb8aa3b, v11
	v_cvt_pk_bf16_f32 v27, v28, v40
	s_waitcnt lgkmcnt(0)
; __device__ __forceinline__ void rwkv_prep_task(KP p, int l, int tile, int hg, bf16_t* sAp) {
;     ...
;     ss += __shfl_xor(ss, 16); ss += __shfl_xor(ss, 32);
;     bon += __shfl_xor(bon, 16); bon += __shfl_xor(bon, 32);
;     const float inv = rsqrtf(ss + 1e-12f);
;     const size_t o = (size_t)R * 512 + cb;
; #pragma unroll
;     for (int e4 = 0; e4 < 4; ++e4) *(float4*)(Rw + o + e4 * 4) = make_float4(wd[e4 * 4], wd[e4 * 4 + 1], wd[e4 * 4 + 2], wd[e4 * 4 + 3]);
; #pragma unroll
;     for (int hf = 0; hf < 2; ++hf) {
;         u32x4 vkk, vka, vkp, vr, vv, vg;
; #pragma unroll
;         for (int k = 0; k < 4; ++k) {
;             const int e = hf * 8 + k * 2;
;             const float k0 = kkv[e] * inv, k1 = kkv[e + 1] * inv;
;             vkk[k] = pack2(k0, k1); vka[k] = pack2(k0 * av[e], k1 * av[e + 1]); vkp[k] = pack2(kp[e], kp[e + 1]);
;             vr[k] = pack2(x3[0][e], x3[0][e + 1]); vv[k] = pack2(x3[2][e], x3[2][e + 1]); vg[k] = pack2(gv[e], gv[e + 1]);
;         }
;         *(u32x4*)(Rkk + o + hf * 8) = vkk; *(u32x4*)(Rka + o + hf * 8) = vka; *(u32x4*)(Rkp + o + hf * 8) = vkp;
;         *(u32x4*)(Rr + o + hf * 8) = vr; *(u32x4*)(Rv + o + hf * 8) = vv; *(u32x4*)(Rg + o + hf * 8) = vg;
;     }
;     if (fq == 0) Rc[(size_t)R * 8 + h] = bon;
; __device__ __forceinline__ void phase_prep(KP p, int l, unsigned char* smem) {
;     ...
;     const int gw = blockIdx.x * 4 + wid, nw = gridDim.x * 4;
;     for (int q = gw; q < TPROMPT / 4 + (NTOK - TPROMPT); q += nw) {
;         if (q < TPROMPT / 4) {
;             const int R0 = q * 4;
;             if ((R0 & 2047) == 0) { for (int k = 0; k < 4; ++k) delta_prep_row(p, l, R0 + k); }
;             else delta_prep_quad(p, l, R0);
;         } else delta_prep_row(p, l, TPROMPT + (q - TPROMPT / 4));
	v_add_f32_e32 v6, v5, v23
	ds_bpermute_b32 v24, v119, v6
	v_cvt_pk_bf16_f32 v28, v3, v7
	v_exp_f32_e32 v11, v11
	global_store_dwordx4 v[56:57], v[58:61], off
	global_store_dwordx4 v[56:57], v[78:81], off offset:16
	global_store_dwordx4 v[56:57], v[90:93], off offset:32
	global_store_dwordx4 v[56:57], v[8:11], off offset:48
	v_add_f32_e32 v32, v211, v32
	s_waitcnt lgkmcnt(0)
	v_add_f32_e32 v6, v6, v24
	v_add_f32_e32 v6, 0x2b8cbccc, v6
	v_mul_f32_e32 v20, 0x4b800000, v6
	v_cmp_gt_f32_e32 vcc, s63, v6
	v_cvt_pk_bf16_f32 v71, v180, v182
	v_cvt_pk_bf16_f32 v68, v175, v177
	v_cndmask_b32_e32 v6, v6, v20, vcc
	v_rsq_f32_e32 v20, v6
	v_cvt_pk_bf16_f32 v72, v184, v185
	v_cvt_pk_bf16_f32 v69, v168, v171
	v_cvt_pk_bf16_f32 v73, v187, v210
	v_mul_f32_e32 v3, 0x45800000, v20
	v_cndmask_b32_e32 v20, v20, v3, vcc
	v_pk_mul_f32 v[10:11], v[94:95], v[20:21] op_sel_hi:[1,0]
	v_pk_mul_f32 v[44:45], v[86:87], v[20:21] op_sel_hi:[1,0]
	v_cvt_pk_bf16_f32 v8, v10, v11
	v_pk_mul_f32 v[10:11], v[142:143], v[10:11]
	v_pk_mul_f32 v[14:15], v[14:15], v[44:45]
	v_cvt_pk_bf16_f32 v42, v10, v11
	v_pk_mul_f32 v[10:11], v[88:89], v[20:21] op_sel_hi:[1,0]
	ds_bpermute_b32 v33, v119, v32
	v_cvt_pk_bf16_f32 v9, v10, v11
	v_pk_mul_f32 v[10:11], v[144:145], v[10:11]
	v_cmp_eq_u32_e32 vcc, 0, v153
	v_cvt_pk_bf16_f32 v43, v10, v11
	v_cvt_pk_bf16_f32 v10, v44, v45
	v_cvt_pk_bf16_f32 v44, v14, v15
	v_pk_mul_f32 v[14:15], v[34:35], v[20:21] op_sel_hi:[1,0]
	v_cvt_pk_bf16_f32 v4, v164, v165
	v_cvt_pk_bf16_f32 v11, v14, v15
	v_pk_mul_f32 v[14:15], v[18:19], v[14:15]
	v_pk_mul_f32 v[18:19], v[100:101], v[20:21] op_sel_hi:[1,0]
	v_cvt_pk_bf16_f32 v45, v14, v15
	global_store_dwordx4 v[74:75], v[8:11], off
	global_store_dwordx4 v[76:77], v[42:45], off
	global_store_dwordx4 v[82:83], v[62:65], off
	global_store_dwordx4 v[84:85], v[66:69], off
	global_store_dwordx4 v[104:105], v[70:73], off
	global_store_dwordx4 v[116:117], v[36:39], off
	v_pk_mul_f32 v[10:11], v[102:103], v[20:21] op_sel_hi:[1,0]
	v_pk_mul_f32 v[16:17], v[16:17], v[18:19]
	v_cvt_pk_bf16_f32 v8, v10, v11
	v_pk_mul_f32 v[10:11], v[30:31], v[10:11]
	v_cvt_pk_bf16_f32 v22, v186, v188
	v_cvt_pk_bf16_f32 v14, v10, v11
	v_pk_mul_f32 v[10:11], v[54:55], v[20:21] op_sel_hi:[1,0]
	v_cvt_pk_bf16_f32 v1, v50, v51
	v_cvt_pk_bf16_f32 v9, v10, v11
	v_pk_mul_f32 v[10:11], v[96:97], v[10:11]
	v_cvt_pk_bf16_f32 v5, v166, v169
	v_cvt_pk_bf16_f32 v15, v10, v11
	v_cvt_pk_bf16_f32 v10, v18, v19
	v_pk_mul_f32 v[18:19], v[46:47], v[20:21] op_sel_hi:[1,0]
	v_cvt_pk_bf16_f32 v23, v189, v190
	v_cvt_pk_bf16_f32 v11, v18, v19
	v_pk_mul_f32 v[18:19], v[48:49], v[18:19]
	v_cvt_pk_bf16_f32 v6, v167, v170
	v_cvt_pk_bf16_f32 v24, v191, v209
	v_cvt_pk_bf16_f32 v16, v16, v17
	v_cvt_pk_bf16_f32 v17, v18, v19
	v_cvt_pk_bf16_f32 v3, v52, v53
	v_cvt_pk_bf16_f32 v7, v12, v163
	v_cvt_pk_bf16_f32 v25, v181, v183
	global_store_dwordx4 v[74:75], v[8:11], off offset:16
	global_store_dwordx4 v[76:77], v[14:17], off offset:16
	global_store_dwordx4 v[82:83], v[0:3], off offset:16
	global_store_dwordx4 v[84:85], v[4:7], off offset:16
	global_store_dwordx4 v[104:105], v[22:25], off offset:16
	global_store_dwordx4 v[116:117], v[26:29], off offset:16
	s_and_saveexec_b64 s[12:13], vcc
	s_cbranch_execz .LBB0_346
	v_lshlrev_b64 v[0:1], 5, v[154:155]
	v_lshl_add_u64 v[0:1], s[24:25], 0, v[0:1]
	v_ashrrev_i32_e32 v153, 31, v152
	v_lshl_add_u64 v[0:1], v[152:153], 2, v[0:1]
	s_waitcnt lgkmcnt(0)
	v_add_f32_e32 v2, v32, v33
	global_store_dword v[0:1], v2, off
	s_branch .LBB0_346
.LBB0_421:
	v_ashrrev_i32_e32 v0, 6, v162
	v_readlane_b32 s2, v231, 26
	v_mov_b32_e32 v66, v208
	s_nop 0
	v_add_u32_e32 v94, s2, v0
	s_movk_i32 s2, 0x1400
	v_cmp_gt_i32_e32 vcc, s2, v94
	s_and_saveexec_b64 s[50:51], vcc
	s_cbranch_execz .LBB0_460
	v_readlane_b32 s2, v231, 16
	v_lshrrev_b32_e32 v1, 6, v162
	v_readlane_b32 s12, v230, 25
	v_add_u32_e32 v95, s2, v0
	v_readlane_b32 s2, v231, 26
	s_lshl_b32 s11, s12, 7
	s_lshl_b32 s94, s12, 2
	v_add_u16_e32 v96, s2, v1
	v_readlane_b32 s2, v231, 17
	s_add_u32 s52, s58, 0x28cf3a00
	s_addc_u32 s53, s59, 0
	v_add_u32_e32 v97, s2, v0
	v_lshlrev_b32_e32 v0, 2, v0
	v_readlane_b32 s2, v231, 18
	s_add_u32 s54, s58, 0x28c68000
	s_mul_hi_i32 s78, s12, 0x6000
	v_add_u32_e32 v98, s2, v0
	v_readlane_b32 s2, v231, 20
	s_mul_i32 s79, s12, 0x6000
	s_addc_u32 s55, s59, 0
	v_add_u32_e32 v99, s2, v0
	v_readlane_b32 s2, v231, 21
	s_mov_b64 s[74:75], 0
	v_mov_b32_e32 v66, v208
	v_add_u32_e32 v100, s2, v0
	v_readlane_b32 s2, v231, 24
	v_readlane_b32 s13, v230, 26
	s_nop 0
	v_add_u32_e32 v101, s2, v0
	v_readlane_b32 s2, v231, 22
	s_nop 1
	v_add_u32_e32 v102, s2, v0
	v_readlane_b32 s2, v231, 23
	s_nop 1
	v_add_u32_e32 v103, s2, v0
	v_readlane_b32 s2, v231, 25
	s_nop 1
	v_add_u32_e32 v104, s2, v0
	s_branch .LBB0_424

; __device__ __forceinline__ int tidx() { int t = threadIdx.x; asm volatile("" : "+v"(t)); return t; }
; __device__ __forceinline__ float ldnt(const float* p) { return __builtin_nontemporal_load(p); }
; __device__ __forceinline__ void conv_job(const float* __restrict__ src, int ld, int K, bf16_t* dst, int Ndst, int kind, float* tile) {
;     const int tid_ = tidx();
;     const int tilesK = K >> 6, ntiles = tilesK * (Ndst >> 6);
;     const int tx = tid_ & 63, ty = tid_ >> 6;
;     const int tx2 = tid_ & 31, ty2 = tid_ >> 5;
;     float r[16];
;     int t = blockIdx.x;
;     if (t < ntiles) {
;         const int tk = t % tilesK, tn = t / tilesK, k0 = tk << 6, n0 = tn << 6;
;         const int sc = mapcol(kind, n0 + tx);
; #pragma unroll
;         for (int i = 0; i < 16; ++i) r[i] = sc >= 0 ? ldnt(src + (size_t)(k0 + ty + 4 * i) * ld + sc) : 0.f;
;     }
;     for (; t < ntiles; t += gridDim.x) {
;         const int tk = t % tilesK, tn = t / tilesK, k0 = tk << 6, n0 = tn << 6;
; #pragma unroll
;         for (int i = 0; i < 16; ++i) tile[(ty + 4 * i) * 65 + tx] = r[i];
;         __syncthreads();
;         const int tnext = t + gridDim.x;
;         if (tnext < ntiles) {
;             const int tk2 = tnext % tilesK, tn2 = tnext / tilesK, k2 = tk2 << 6, n2 = tn2 << 6;
;             const int sc = mapcol(kind, n2 + tx);
; #pragma unroll
;             for (int i = 0; i < 16; ++i) r[i] = sc >= 0 ? ldnt(src + (size_t)(k2 + ty + 4 * i) * ld + sc) : 0.f;
;         }
; #pragma unroll
;         for (int i = 0; i < 8; ++i) {
;             const int nn = ty2 + 8 * i;
;             *(unsigned*)(dst + (size_t)(n0 + nn) * K + k0 + 2 * tx2) = pack2(tile[(2 * tx2) * 65 + nn], tile[(2 * tx2 + 1) * 65 + nn]);
;         }
;         __syncthreads();
;     }
; }
; __device__ __forceinline__ void convert_layer_weights(KP p, int l, float* tile) {
;     ...
;     conv_job(p->in[I_F1I] + (size_t)l * 1024 * 4096, 4096, 1024, (bf16_t*)(ws + OFF_WF1I), 4096, 1, tile);
.LBB0_616:
	s_and_b64 vcc, exec, s[14:15]
	v_mov_b32_e32 v66, v208
	s_cbranch_vccz .LBB0_1475
	v_and_b32_e32 v54, 7, v193
	v_lshrrev_b32_e32 v55, 3, v193
	v_lshrrev_b32_e32 v56, 6, v192
	v_mul_u32_u24_e32 v56, 0x1200, v56
	v_mul_u32_u24_e32 v52, 0x90, v55
	v_lshl_add_u32 v52, v54, 4, v52
	v_add_u32_e32 v52, v56, v52
	v_lshl_add_u32 v56, v55, 4, v56
	v_readlane_b32 s12, v230, 25
	v_readlane_b32 s14, v230, 23
	v_readlane_b32 s15, v230, 24
	s_add_i32 s19, s12, 1
	s_and_b64 s[14:15], exec, s[14:15]
	s_cselect_b32 s19, 0, s19
	v_readlane_b32 s18, v231, 56
	s_lshl_b32 s18, s18, 2
	v_lshrrev_b32_e32 v53, 6, v192
	s_nop 0
	v_readfirstlane_b32 s2, v53
	s_add_i32 s18, s18, s2
	v_mul_u32_u24_e32 v50, 0x20000, v55
	v_lshl_add_u32 v50, v54, 4, v50
	v_lshrrev_b32_e32 v53, 2, v54
	v_mul_u32_u24_e32 v51, 0x1fc0, v53
	v_add_u32_e32 v50, v50, v51
	v_and_b32_e32 v51, 3, v54
	v_mul_u32_u24_e32 v51, 0x480, v51
	v_mul_u32_u24_e32 v53, 0x90, v53
	v_add3_u32 v51, v51, v53, v56
	v_mul_u32_u24_e32 v53, 0x800, v55
	v_lshl_add_u32 v53, v54, 4, v53
	s_load_dwordx2 s[22:23], s[16:17], 0xf8
	s_mul_i32 s12, s19, 0x1000000
	s_waitcnt lgkmcnt(0)
	s_add_u32 s22, s22, s12
	s_addc_u32 s23, s23, 0
	s_add_u32 s24, s58, 0x0
	s_addc_u32 s25, s59, 0
	s_sub_i32 s2, s18, 0x0
	s_and_b32 s2, s2, 0x7ff
	s_cmp_lt_u32 s2, 0x800
	s_cbranch_scc0 .Lcv_f1i_done
.Lcv_f1i_loop:
	s_and_b32 s11, s2, 0xf
	s_lshr_b32 s12, s2, 4
	s_mul_i32 s13, s11, 0x100000
	s_lshl_b32 s14, s12, 6
	s_add_u32 s13, s13, s14
	s_add_u32 s40, s22, s13
	s_addc_u32 s41, s23, 0
	global_load_dwordx4 v[0:3], v50, s[40:41] nt
	s_add_u32 s40, s40, 0x4000
	s_addc_u32 s41, s41, 0
	global_load_dwordx4 v[4:7], v50, s[40:41] nt
	s_add_u32 s40, s40, 0x4000
	s_addc_u32 s41, s41, 0
	global_load_dwordx4 v[8:11], v50, s[40:41] nt
	s_add_u32 s40, s40, 0x4000
	s_addc_u32 s41, s41, 0
	global_load_dwordx4 v[14:17], v50, s[40:41] nt
	s_add_u32 s40, s40, 0x4000
	s_addc_u32 s41, s41, 0
	global_load_dwordx4 v[18:21], v50, s[40:41] nt
	s_add_u32 s40, s40, 0x4000
	s_addc_u32 s41, s41, 0
	global_load_dwordx4 v[22:25], v50, s[40:41] nt
	s_add_u32 s40, s40, 0x4000
	s_addc_u32 s41, s41, 0
	global_load_dwordx4 v[26:29], v50, s[40:41] nt
	s_add_u32 s40, s40, 0x4000
	s_addc_u32 s41, s41, 0
	global_load_dwordx4 v[30:33], v50, s[40:41] nt
	s_add_u32 s40, s40, 0x4000
	s_addc_u32 s41, s41, 0
	s_mul_i32 s13, s12, 0x10000
	s_lshl_b32 s14, s11, 7
	s_add_u32 s13, s13, s14
	s_add_u32 s42, s24, s13
	s_addc_u32 s43, s25, 0
	s_waitcnt vmcnt(0)
	v_cvt_pk_bf16_f32 v34, v0, v4
	v_cvt_pk_bf16_f32 v35, v8, v14
	v_cvt_pk_bf16_f32 v36, v18, v22
	v_cvt_pk_bf16_f32 v37, v26, v30
	v_cvt_pk_bf16_f32 v38, v1, v5
	v_cvt_pk_bf16_f32 v39, v9, v15
	v_cvt_pk_bf16_f32 v40, v19, v23
	v_cvt_pk_bf16_f32 v41, v27, v31
	v_cvt_pk_bf16_f32 v42, v2, v6
	v_cvt_pk_bf16_f32 v43, v10, v16
	v_cvt_pk_bf16_f32 v44, v20, v24
	v_cvt_pk_bf16_f32 v45, v28, v32
	v_cvt_pk_bf16_f32 v46, v3, v7
	v_cvt_pk_bf16_f32 v47, v11, v17
	v_cvt_pk_bf16_f32 v48, v21, v25
	v_cvt_pk_bf16_f32 v49, v29, v33
	ds_write_b128 v51, v[34:37] offset:0
	ds_write_b128 v51, v[38:41] offset:288
	ds_write_b128 v51, v[42:45] offset:576
	ds_write_b128 v51, v[46:49] offset:864
	s_waitcnt lgkmcnt(0)
	ds_read_b128 v[34:37], v52 offset:0
	ds_read_b128 v[38:41], v52 offset:1152
	ds_read_b128 v[42:45], v52 offset:2304
	ds_read_b128 v[46:49], v52 offset:3456
	s_waitcnt lgkmcnt(0)
	global_store_dwordx4 v53, v[34:37], s[42:43]
	s_add_u32 s42, s42, 0x4000
	s_addc_u32 s43, s43, 0
	global_store_dwordx4 v53, v[38:41], s[42:43]
	s_add_u32 s42, s42, 0x4000
	s_addc_u32 s43, s43, 0
	global_store_dwordx4 v53, v[42:45], s[42:43]
	s_add_u32 s42, s42, 0x4000
	s_addc_u32 s43, s43, 0
	global_store_dwordx4 v53, v[46:49], s[42:43]
	s_addk_i32 s2, 0x800
	s_cmp_lt_u32 s2, 0x800
	s_cbranch_scc1 .Lcv_f1i_loop
; __device__ __forceinline__ int tidx() { int t = threadIdx.x; asm volatile("" : "+v"(t)); return t; }
; __device__ __forceinline__ float ldnt(const float* p) { return __builtin_nontemporal_load(p); }
; __device__ __forceinline__ void conv_job(const float* __restrict__ src, int ld, int K, bf16_t* dst, int Ndst, int kind, float* tile) {
;     const int tid_ = tidx();
;     const int tilesK = K >> 6, ntiles = tilesK * (Ndst >> 6);
;     const int tx = tid_ & 63, ty = tid_ >> 6;
;     const int tx2 = tid_ & 31, ty2 = tid_ >> 5;
;     float r[16];
;     int t = blockIdx.x;
;     if (t < ntiles) {
;         const int tk = t % tilesK, tn = t / tilesK, k0 = tk << 6, n0 = tn << 6;
;         const int sc = mapcol(kind, n0 + tx);
; #pragma unroll
;         for (int i = 0; i < 16; ++i) r[i] = sc >= 0 ? ldnt(src + (size_t)(k0 + ty + 4 * i) * ld + sc) : 0.f;
;     }
;     for (; t < ntiles; t += gridDim.x) {
;         const int tk = t % tilesK, tn = t / tilesK, k0 = tk << 6, n0 = tn << 6;
; #pragma unroll
;         for (int i = 0; i < 16; ++i) tile[(ty + 4 * i) * 65 + tx] = r[i];
;         __syncthreads();
;         const int tnext = t + gridDim.x;
;         if (tnext < ntiles) {
;             const int tk2 = tnext % tilesK, tn2 = tnext / tilesK, k2 = tk2 << 6, n2 = tn2 << 6;
;             const int sc = mapcol(kind, n2 + tx);
; #pragma unroll
;             for (int i = 0; i < 16; ++i) r[i] = sc >= 0 ? ldnt(src + (size_t)(k2 + ty + 4 * i) * ld + sc) : 0.f;
;         }
; #pragma unroll
;         for (int i = 0; i < 8; ++i) {
;             const int nn = ty2 + 8 * i;
;             *(unsigned*)(dst + (size_t)(n0 + nn) * K + k0 + 2 * tx2) = pack2(tile[(2 * tx2) * 65 + nn], tile[(2 * tx2 + 1) * 65 + nn]);
;         }
;         __syncthreads();
;     }
; }
; __device__ __forceinline__ void convert_layer_weights(KP p, int l, float* tile) {
;     ...
;     conv_job(p->in[I_F1O] + (size_t)l * 2048 * 1024, 1024, 2048, (bf16_t*)(ws + OFF_WF1O), 1024, 0, tile);
;     conv_job(p->in[I_F2I] + (size_t)l * 1024 * 4096, 4096, 1024, (bf16_t*)(ws + OFF_WF2I), 4096, 1, tile);
.Lcv_f1i_done:
	v_mul_u32_u24_e32 v50, 0x8000, v55
	v_lshl_add_u32 v50, v54, 4, v50
	v_mul_u32_u24_e32 v51, 0x240, v54
	v_add_u32_e32 v51, v51, v56
	v_mul_u32_u24_e32 v53, 0x1000, v55
	v_lshl_add_u32 v53, v54, 4, v53
	s_load_dwordx2 s[22:23], s[16:17], 0x100
	s_mul_i32 s12, s19, 0x800000
	s_waitcnt lgkmcnt(0)
	s_add_u32 s22, s22, s12
	s_addc_u32 s23, s23, 0
	s_add_u32 s24, s58, 0x800000
	s_addc_u32 s25, s59, 0
	s_sub_i32 s2, s18, 0x0
	s_and_b32 s2, s2, 0x7ff
	s_cmp_lt_u32 s2, 0x400
	s_cbranch_scc0 .Lcv_f1o_done
.Lcv_f1o_loop:
	s_and_b32 s11, s2, 0x1f
	s_lshr_b32 s12, s2, 5
	s_mul_i32 s13, s11, 0x40000
	s_lshl_b32 s14, s12, 7
	s_add_u32 s13, s13, s14
	s_add_u32 s40, s22, s13
	s_addc_u32 s41, s23, 0
	global_load_dwordx4 v[0:3], v50, s[40:41] nt
	s_add_u32 s40, s40, 0x1000
	s_addc_u32 s41, s41, 0
	global_load_dwordx4 v[4:7], v50, s[40:41] nt
	s_add_u32 s40, s40, 0x1000
	s_addc_u32 s41, s41, 0
	global_load_dwordx4 v[8:11], v50, s[40:41] nt
	s_add_u32 s40, s40, 0x1000
	s_addc_u32 s41, s41, 0
	global_load_dwordx4 v[14:17], v50, s[40:41] nt
	s_add_u32 s40, s40, 0x1000
	s_addc_u32 s41, s41, 0
	global_load_dwordx4 v[18:21], v50, s[40:41] nt
	s_add_u32 s40, s40, 0x1000
	s_addc_u32 s41, s41, 0
	global_load_dwordx4 v[22:25], v50, s[40:41] nt
	s_add_u32 s40, s40, 0x1000
	s_addc_u32 s41, s41, 0
	global_load_dwordx4 v[26:29], v50, s[40:41] nt
	s_add_u32 s40, s40, 0x1000
	s_addc_u32 s41, s41, 0
	global_load_dwordx4 v[30:33], v50, s[40:41] nt
	s_add_u32 s40, s40, 0x1000
	s_addc_u32 s41, s41, 0
	s_mul_i32 s13, s12, 0x20000
	s_lshl_b32 s14, s11, 7
	s_add_u32 s13, s13, s14
	s_add_u32 s42, s24, s13
	s_addc_u32 s43, s25, 0
	s_waitcnt vmcnt(0)
	v_cvt_pk_bf16_f32 v34, v0, v4
	v_cvt_pk_bf16_f32 v35, v8, v14
	v_cvt_pk_bf16_f32 v36, v18, v22
	v_cvt_pk_bf16_f32 v37, v26, v30
	v_cvt_pk_bf16_f32 v38, v1, v5
	v_cvt_pk_bf16_f32 v39, v9, v15
	v_cvt_pk_bf16_f32 v40, v19, v23
	v_cvt_pk_bf16_f32 v41, v27, v31
	v_cvt_pk_bf16_f32 v42, v2, v6
	v_cvt_pk_bf16_f32 v43, v10, v16
	v_cvt_pk_bf16_f32 v44, v20, v24
	v_cvt_pk_bf16_f32 v45, v28, v32
	v_cvt_pk_bf16_f32 v46, v3, v7
	v_cvt_pk_bf16_f32 v47, v11, v17
	v_cvt_pk_bf16_f32 v48, v21, v25
	v_cvt_pk_bf16_f32 v49, v29, v33
	ds_write_b128 v51, v[34:37] offset:0
	ds_write_b128 v51, v[38:41] offset:144
	ds_write_b128 v51, v[42:45] offset:288
	ds_write_b128 v51, v[46:49] offset:432
	s_waitcnt lgkmcnt(0)
	ds_read_b128 v[34:37], v52 offset:0
	ds_read_b128 v[38:41], v52 offset:1152
	ds_read_b128 v[42:45], v52 offset:2304
	ds_read_b128 v[46:49], v52 offset:3456
	s_waitcnt lgkmcnt(0)
	global_store_dwordx4 v53, v[34:37], s[42:43]
	s_add_u32 s42, s42, 0x8000
	s_addc_u32 s43, s43, 0
	global_store_dwordx4 v53, v[38:41], s[42:43]
	s_add_u32 s42, s42, 0x8000
	s_addc_u32 s43, s43, 0
	global_store_dwordx4 v53, v[42:45], s[42:43]
	s_add_u32 s42, s42, 0x8000
	s_addc_u32 s43, s43, 0
	global_store_dwordx4 v53, v[46:49], s[42:43]
	s_addk_i32 s2, 0x800
	s_cmp_lt_u32 s2, 0x400
	s_cbranch_scc1 .Lcv_f1o_loop
.Lcv_f1o_done:
	v_mul_u32_u24_e32 v50, 0x20000, v55
	v_lshl_add_u32 v50, v54, 4, v50
	v_lshrrev_b32_e32 v53, 2, v54
	v_mul_u32_u24_e32 v51, 0x1fc0, v53
	v_add_u32_e32 v50, v50, v51
	v_and_b32_e32 v51, 3, v54
	v_mul_u32_u24_e32 v51, 0x480, v51
	v_mul_u32_u24_e32 v53, 0x90, v53
	v_add3_u32 v51, v51, v53, v56
	v_mul_u32_u24_e32 v53, 0x800, v55
	v_lshl_add_u32 v53, v54, 4, v53
	s_load_dwordx2 s[22:23], s[16:17], 0x108
	s_mul_i32 s12, s19, 0x1000000
	s_waitcnt lgkmcnt(0)
	s_add_u32 s22, s22, s12
	s_addc_u32 s23, s23, 0
	s_add_u32 s24, s58, 0xc00000
	s_addc_u32 s25, s59, 0
	s_sub_i32 s2, s18, 0x400
	s_and_b32 s2, s2, 0x7ff
	s_cmp_lt_u32 s2, 0x800
	s_cbranch_scc0 .Lcv_f2i_done

; __device__ __forceinline__ void convert_layer_weights(KP p, int l, float* tile) {
;     ...
;     conv_job(p->in[I_F2O] + (size_t)l * 2048 * 1024, 1024, 2048, (bf16_t*)(ws + OFF_WF2O), 1024, 0, tile);
.Lcv_f2i_done:
	v_mul_u32_u24_e32 v50, 0x8000, v55
	v_lshl_add_u32 v50, v54, 4, v50
	v_mul_u32_u24_e32 v51, 0x240, v54
	v_add_u32_e32 v51, v51, v56
	v_mul_u32_u24_e32 v53, 0x1000, v55
	v_lshl_add_u32 v53, v54, 4, v53
	s_load_dwordx2 s[22:23], s[16:17], 0x110
	s_mul_i32 s12, s19, 0x800000
	s_waitcnt lgkmcnt(0)
	s_add_u32 s22, s22, s12
	s_addc_u32 s23, s23, 0
	s_add_u32 s24, s58, 0x1400000
	s_addc_u32 s25, s59, 0
	s_sub_i32 s2, s18, 0x400
	s_and_b32 s2, s2, 0x7ff
	s_cmp_lt_u32 s2, 0x400
	s_cbranch_scc0 .Lcv_f2o_done

; __device__ __forceinline__ int tidx() { int t = threadIdx.x; asm volatile("" : "+v"(t)); return t; }
; __device__ __forceinline__ float ldnt(const float* p) { return __builtin_nontemporal_load(p); }
; __device__ __forceinline__ void conv_job(const float* __restrict__ src, int ld, int K, bf16_t* dst, int Ndst, int kind, float* tile) {
;     const int tid_ = tidx();
;     const int tilesK = K >> 6, ntiles = tilesK * (Ndst >> 6);
;     const int tx = tid_ & 63, ty = tid_ >> 6;
;     const int tx2 = tid_ & 31, ty2 = tid_ >> 5;
;     float r[16];
;     int t = blockIdx.x;
;     if (t < ntiles) {
;         const int tk = t % tilesK, tn = t / tilesK, k0 = tk << 6, n0 = tn << 6;
;         const int sc = mapcol(kind, n0 + tx);
; #pragma unroll
;         for (int i = 0; i < 16; ++i) r[i] = sc >= 0 ? ldnt(src + (size_t)(k0 + ty + 4 * i) * ld + sc) : 0.f;
;     }
;     for (; t < ntiles; t += gridDim.x) {
;         const int tk = t % tilesK, tn = t / tilesK, k0 = tk << 6, n0 = tn << 6;
; #pragma unroll
;         for (int i = 0; i < 16; ++i) tile[(ty + 4 * i) * 65 + tx] = r[i];
;         __syncthreads();
;         const int tnext = t + gridDim.x;
;         if (tnext < ntiles) {
;             const int tk2 = tnext % tilesK, tn2 = tnext / tilesK, k2 = tk2 << 6, n2 = tn2 << 6;
;             const int sc = mapcol(kind, n2 + tx);
; #pragma unroll
;             for (int i = 0; i < 16; ++i) r[i] = sc >= 0 ? ldnt(src + (size_t)(k2 + ty + 4 * i) * ld + sc) : 0.f;
;         }
; #pragma unroll
;         for (int i = 0; i < 8; ++i) {
;             const int nn = ty2 + 8 * i;
;             *(unsigned*)(dst + (size_t)(n0 + nn) * K + k0 + 2 * tx2) = pack2(tile[(2 * tx2) * 65 + nn], tile[(2 * tx2 + 1) * 65 + nn]);
;         }
;         __syncthreads();
;     }
; }
; __device__ __forceinline__ void convert_layer_weights(KP p, int l, float* tile) {
;     ...
;     conv_job(p->in[I_WIN] + (size_t)l * 1024 * 8712, 8712, 1024, (bf16_t*)(ws + OFF_WP), PW, 2, tile);
;     conv_job(p->in[I_WIN] + (size_t)l * 1024 * 8712, 8712, 1024, (bf16_t*)(ws + OFF_WG), 4096, 3, tile);
.Lcv_f2o_done:
	v_mul_u32_u24_e32 v50, 0x44100, v55
	v_lshl_add_u32 v50, v54, 4, v50
	v_mul_u32_u24_e32 v51, 0x240, v54
	v_add_u32_e32 v51, v51, v56
	v_mul_u32_u24_e32 v53, 0x800, v55
	v_lshl_add_u32 v53, v54, 4, v53
	s_load_dwordx2 s[22:23], s[16:17], 0x50
	s_mul_i32 s12, s19, 0x2208000
	s_waitcnt lgkmcnt(0)
	s_add_u32 s22, s22, s12
	s_addc_u32 s23, s23, 0
	s_add_u32 s24, s58, 0x1800000
	s_addc_u32 s25, s59, 0
	s_sub_i32 s2, s18, 0x0
	s_and_b32 s2, s2, 0x7ff
	s_cmp_lt_u32 s2, 0x940
	s_cbranch_scc0 .Lcv_wp_done
.Lcv_wp_loop:
	s_and_b32 s11, s2, 0xf
	s_lshr_b32 s12, s2, 4
	s_mul_i32 s13, s11, 0x220800
	s_lshl_b32 s14, s12, 7
	s_cmp_lt_u32 s12, 136
	s_cbranch_scc1 .Lcv_wp_col
	s_add_u32 s14, s14, 32
	s_cmp_lt_u32 s12, 144
	s_cbranch_scc1 .Lcv_wp_col
	v_mov_b32_e32 v0, 0
	v_mov_b32_e32 v1, 0
	v_mov_b32_e32 v2, 0
	v_mov_b32_e32 v3, 0
	v_mov_b32_e32 v4, 0
	v_mov_b32_e32 v5, 0
	v_mov_b32_e32 v6, 0
	v_mov_b32_e32 v7, 0
	v_mov_b32_e32 v8, 0
	v_mov_b32_e32 v9, 0
	v_mov_b32_e32 v10, 0
	v_mov_b32_e32 v11, 0
	v_mov_b32_e32 v14, 0
	v_mov_b32_e32 v15, 0
	v_mov_b32_e32 v16, 0
	v_mov_b32_e32 v17, 0
	v_mov_b32_e32 v18, 0
	v_mov_b32_e32 v19, 0
	v_mov_b32_e32 v20, 0
	v_mov_b32_e32 v21, 0
	v_mov_b32_e32 v22, 0
	v_mov_b32_e32 v23, 0
	v_mov_b32_e32 v24, 0
	v_mov_b32_e32 v25, 0
	v_mov_b32_e32 v26, 0
	v_mov_b32_e32 v27, 0
	v_mov_b32_e32 v28, 0
	v_mov_b32_e32 v29, 0
	v_mov_b32_e32 v30, 0
	v_mov_b32_e32 v31, 0
	v_mov_b32_e32 v32, 0
	v_mov_b32_e32 v33, 0
	s_cmp_eq_u32 s12, 144
	s_cbranch_scc0 .Lcv_wp_pack
	s_movk_i32 s14, 0x4400
	s_add_u32 s13, s13, s14
	s_add_u32 s40, s22, s13
	s_addc_u32 s41, s23, 0
	v_cmp_gt_u32_e32 vcc, 2, v54
	s_and_saveexec_b64 s[14:15], vcc
	global_load_dwordx4 v[0:3], v50, s[40:41] nt
	s_add_u32 s40, s40, 0x8820
	s_addc_u32 s41, s41, 0
	global_load_dwordx4 v[4:7], v50, s[40:41] nt
	s_add_u32 s40, s40, 0x8820
	s_addc_u32 s41, s41, 0
	global_load_dwordx4 v[8:11], v50, s[40:41] nt
	s_add_u32 s40, s40, 0x8820
	s_addc_u32 s41, s41, 0
	global_load_dwordx4 v[14:17], v50, s[40:41] nt
	s_add_u32 s40, s40, 0x8820
	s_addc_u32 s41, s41, 0
	global_load_dwordx4 v[18:21], v50, s[40:41] nt
	s_add_u32 s40, s40, 0x8820
	s_addc_u32 s41, s41, 0
	global_load_dwordx4 v[22:25], v50, s[40:41] nt
	s_add_u32 s40, s40, 0x8820
	s_addc_u32 s41, s41, 0
	global_load_dwordx4 v[26:29], v50, s[40:41] nt
	s_add_u32 s40, s40, 0x8820
	s_addc_u32 s41, s41, 0
	global_load_dwordx4 v[30:33], v50, s[40:41] nt
	s_add_u32 s40, s40, 0x8820
	s_addc_u32 s41, s41, 0
	s_or_b64 exec, exec, s[14:15]
	s_branch .Lcv_wp_pack
.Lcv_wp_col:
	s_add_u32 s13, s13, s14
	s_add_u32 s40, s22, s13
	s_addc_u32 s41, s23, 0
	global_load_dwordx4 v[0:3], v50, s[40:41] nt
	s_add_u32 s40, s40, 0x8820
	s_addc_u32 s41, s41, 0
	global_load_dwordx4 v[4:7], v50, s[40:41] nt
	s_add_u32 s40, s40, 0x8820
	s_addc_u32 s41, s41, 0
	global_load_dwordx4 v[8:11], v50, s[40:41] nt
	s_add_u32 s40, s40, 0x8820
	s_addc_u32 s41, s41, 0
	global_load_dwordx4 v[14:17], v50, s[40:41] nt
	s_add_u32 s40, s40, 0x8820
	s_addc_u32 s41, s41, 0
	global_load_dwordx4 v[18:21], v50, s[40:41] nt
	s_add_u32 s40, s40, 0x8820
	s_addc_u32 s41, s41, 0
	global_load_dwordx4 v[22:25], v50, s[40:41] nt
	s_add_u32 s40, s40, 0x8820
	s_addc_u32 s41, s41, 0
	global_load_dwordx4 v[26:29], v50, s[40:41] nt
	s_add_u32 s40, s40, 0x8820
	s_addc_u32 s41, s41, 0
	global_load_dwordx4 v[30:33], v50, s[40:41] nt
	s_add_u32 s40, s40, 0x8820
	s_addc_u32 s41, s41, 0
.Lcv_wp_pack:
	s_mul_i32 s13, s12, 0x10000
	s_lshl_b32 s14, s11, 7
	s_add_u32 s13, s13, s14
	s_add_u32 s42, s24, s13
	s_addc_u32 s43, s25, 0
	s_waitcnt vmcnt(0)
	v_cvt_pk_bf16_f32 v34, v0, v4
	v_cvt_pk_bf16_f32 v35, v8, v14
	v_cvt_pk_bf16_f32 v36, v18, v22
	v_cvt_pk_bf16_f32 v37, v26, v30
	v_cvt_pk_bf16_f32 v38, v1, v5
	v_cvt_pk_bf16_f32 v39, v9, v15
	v_cvt_pk_bf16_f32 v40, v19, v23
	v_cvt_pk_bf16_f32 v41, v27, v31
	v_cvt_pk_bf16_f32 v42, v2, v6
	v_cvt_pk_bf16_f32 v43, v10, v16
	v_cvt_pk_bf16_f32 v44, v20, v24
	v_cvt_pk_bf16_f32 v45, v28, v32
	v_cvt_pk_bf16_f32 v46, v3, v7
	v_cvt_pk_bf16_f32 v47, v11, v17
	v_cvt_pk_bf16_f32 v48, v21, v25
	v_cvt_pk_bf16_f32 v49, v29, v33
	ds_write_b128 v51, v[34:37] offset:0
	ds_write_b128 v51, v[38:41] offset:144
	ds_write_b128 v51, v[42:45] offset:288
	ds_write_b128 v51, v[46:49] offset:432
	s_waitcnt lgkmcnt(0)
	ds_read_b128 v[34:37], v52 offset:0
	ds_read_b128 v[38:41], v52 offset:1152
	ds_read_b128 v[42:45], v52 offset:2304
	ds_read_b128 v[46:49], v52 offset:3456
	s_waitcnt lgkmcnt(0)
	global_store_dwordx4 v53, v[34:37], s[42:43]
	s_add_u32 s42, s42, 0x4000
	s_addc_u32 s43, s43, 0
	global_store_dwordx4 v53, v[38:41], s[42:43]
	s_add_u32 s42, s42, 0x4000
	s_addc_u32 s43, s43, 0
	global_store_dwordx4 v53, v[42:45], s[42:43]
	s_add_u32 s42, s42, 0x4000
	s_addc_u32 s43, s43, 0
	global_store_dwordx4 v53, v[46:49], s[42:43]
	s_addk_i32 s2, 0x800
	s_cmp_lt_u32 s2, 0x940
	s_cbranch_scc1 .Lcv_wp_loop
.Lcv_wp_done:
	v_mul_u32_u24_e32 v50, 0x44100, v55
	v_lshl_add_u32 v50, v54, 4, v50
	v_mul_u32_u24_e32 v51, 0x240, v54
	v_add_u32_e32 v51, v51, v56
	v_mul_u32_u24_e32 v53, 0x800, v55
	v_lshl_add_u32 v53, v54, 4, v53
	s_load_dwordx2 s[22:23], s[16:17], 0x50
	s_mul_i32 s12, s19, 0x2208000
	s_waitcnt lgkmcnt(0)
	s_add_u32 s22, s22, s12
	s_addc_u32 s23, s23, 0
	s_add_u32 s24, s58, 0x2140000
	s_addc_u32 s25, s59, 0
	s_sub_i32 s2, s18, 0x140
	s_and_b32 s2, s2, 0x7ff
	s_cmp_lt_u32 s2, 0x800
	s_cbranch_scc0 .Lcv_wg_done
; __device__ __forceinline__ int tidx() { int t = threadIdx.x; asm volatile("" : "+v"(t)); return t; }
; __device__ __forceinline__ float ldnt(const float* p) { return __builtin_nontemporal_load(p); }
; __device__ __forceinline__ void conv_job(const float* __restrict__ src, int ld, int K, bf16_t* dst, int Ndst, int kind, float* tile) {
;     const int tid_ = tidx();
;     const int tilesK = K >> 6, ntiles = tilesK * (Ndst >> 6);
;     const int tx = tid_ & 63, ty = tid_ >> 6;
;     const int tx2 = tid_ & 31, ty2 = tid_ >> 5;
;     float r[16];
;     int t = blockIdx.x;
;     if (t < ntiles) {
;         const int tk = t % tilesK, tn = t / tilesK, k0 = tk << 6, n0 = tn << 6;
;         const int sc = mapcol(kind, n0 + tx);
; #pragma unroll
;         for (int i = 0; i < 16; ++i) r[i] = sc >= 0 ? ldnt(src + (size_t)(k0 + ty + 4 * i) * ld + sc) : 0.f;
;     }
;     for (; t < ntiles; t += gridDim.x) {
;         const int tk = t % tilesK, tn = t / tilesK, k0 = tk << 6, n0 = tn << 6;
; #pragma unroll
;         for (int i = 0; i < 16; ++i) tile[(ty + 4 * i) * 65 + tx] = r[i];
;         __syncthreads();
;         const int tnext = t + gridDim.x;
;         if (tnext < ntiles) {
;             const int tk2 = tnext % tilesK, tn2 = tnext / tilesK, k2 = tk2 << 6, n2 = tn2 << 6;
;             const int sc = mapcol(kind, n2 + tx);
; #pragma unroll
;             for (int i = 0; i < 16; ++i) r[i] = sc >= 0 ? ldnt(src + (size_t)(k2 + ty + 4 * i) * ld + sc) : 0.f;
;         }
; #pragma unroll
;         for (int i = 0; i < 8; ++i) {
;             const int nn = ty2 + 8 * i;
;             *(unsigned*)(dst + (size_t)(n0 + nn) * K + k0 + 2 * tx2) = pack2(tile[(2 * tx2) * 65 + nn], tile[(2 * tx2 + 1) * 65 + nn]);
;         }
;         __syncthreads();
;     }
; }
; __device__ __forceinline__ void convert_layer_weights(KP p, int l, float* tile) {
;     ...
;     conv_job(p->in[I_WIN] + (size_t)l * 1024 * 8712, 8712, 1024, (bf16_t*)(ws + OFF_WG), 4096, 3, tile);
;     conv_job(p->in[I_WBR] + (size_t)l * 1792 * 1024, 1024, 1792, (bf16_t*)(ws + OFF_WB), 1024, 0, tile);
.Lcv_wg_loop:
	s_and_b32 s11, s2, 0xf
	s_lshr_b32 s12, s2, 4
	s_mul_i32 s13, s11, 0x220800
	s_lshl_b32 s14, s12, 7
	s_add_u32 s14, s14, 0x4820
	s_add_u32 s13, s13, s14
	s_add_u32 s40, s22, s13
	s_addc_u32 s41, s23, 0
	global_load_dwordx4 v[0:3], v50, s[40:41] nt
	s_add_u32 s40, s40, 0x8820
	s_addc_u32 s41, s41, 0
	global_load_dwordx4 v[4:7], v50, s[40:41] nt
	s_add_u32 s40, s40, 0x8820
	s_addc_u32 s41, s41, 0
	global_load_dwordx4 v[8:11], v50, s[40:41] nt
	s_add_u32 s40, s40, 0x8820
	s_addc_u32 s41, s41, 0
	global_load_dwordx4 v[14:17], v50, s[40:41] nt
	s_add_u32 s40, s40, 0x8820
	s_addc_u32 s41, s41, 0
	global_load_dwordx4 v[18:21], v50, s[40:41] nt
	s_add_u32 s40, s40, 0x8820
	s_addc_u32 s41, s41, 0
	global_load_dwordx4 v[22:25], v50, s[40:41] nt
	s_add_u32 s40, s40, 0x8820
	s_addc_u32 s41, s41, 0
	global_load_dwordx4 v[26:29], v50, s[40:41] nt
	s_add_u32 s40, s40, 0x8820
	s_addc_u32 s41, s41, 0
	global_load_dwordx4 v[30:33], v50, s[40:41] nt
	s_add_u32 s40, s40, 0x8820
	s_addc_u32 s41, s41, 0
	s_mul_i32 s13, s12, 0x10000
	s_lshl_b32 s14, s11, 7
	s_add_u32 s13, s13, s14
	s_add_u32 s42, s24, s13
	s_addc_u32 s43, s25, 0
	s_waitcnt vmcnt(0)
	v_cvt_pk_bf16_f32 v34, v0, v4
	v_cvt_pk_bf16_f32 v35, v8, v14
	v_cvt_pk_bf16_f32 v36, v18, v22
	v_cvt_pk_bf16_f32 v37, v26, v30
	v_cvt_pk_bf16_f32 v38, v1, v5
	v_cvt_pk_bf16_f32 v39, v9, v15
	v_cvt_pk_bf16_f32 v40, v19, v23
	v_cvt_pk_bf16_f32 v41, v27, v31
	v_cvt_pk_bf16_f32 v42, v2, v6
	v_cvt_pk_bf16_f32 v43, v10, v16
	v_cvt_pk_bf16_f32 v44, v20, v24
	v_cvt_pk_bf16_f32 v45, v28, v32
	v_cvt_pk_bf16_f32 v46, v3, v7
	v_cvt_pk_bf16_f32 v47, v11, v17
	v_cvt_pk_bf16_f32 v48, v21, v25
	v_cvt_pk_bf16_f32 v49, v29, v33
	ds_write_b128 v51, v[34:37] offset:0
	ds_write_b128 v51, v[38:41] offset:144
	ds_write_b128 v51, v[42:45] offset:288
	ds_write_b128 v51, v[46:49] offset:432
	s_waitcnt lgkmcnt(0)
	ds_read_b128 v[34:37], v52 offset:0
	ds_read_b128 v[38:41], v52 offset:1152
	ds_read_b128 v[42:45], v52 offset:2304
	ds_read_b128 v[46:49], v52 offset:3456
	s_waitcnt lgkmcnt(0)
	global_store_dwordx4 v53, v[34:37], s[42:43]
	s_add_u32 s42, s42, 0x4000
	s_addc_u32 s43, s43, 0
	global_store_dwordx4 v53, v[38:41], s[42:43]
	s_add_u32 s42, s42, 0x4000
	s_addc_u32 s43, s43, 0
	global_store_dwordx4 v53, v[42:45], s[42:43]
	s_add_u32 s42, s42, 0x4000
	s_addc_u32 s43, s43, 0
	global_store_dwordx4 v53, v[46:49], s[42:43]
	s_addk_i32 s2, 0x800
	s_cmp_lt_u32 s2, 0x800
	s_cbranch_scc1 .Lcv_wg_loop
.Lcv_wg_done:
	v_mul_u32_u24_e32 v50, 0x8000, v55
	v_lshl_add_u32 v50, v54, 4, v50
	v_mul_u32_u24_e32 v51, 0x240, v54
	v_add_u32_e32 v51, v51, v56
	v_mul_u32_u24_e32 v53, 0xe00, v55
	v_lshl_add_u32 v53, v54, 4, v53
	s_load_dwordx2 s[22:23], s[16:17], 0xe8
	s_mul_i32 s12, s19, 0x700000
	s_waitcnt lgkmcnt(0)
	s_add_u32 s22, s22, s12
	s_addc_u32 s23, s23, 0
	s_add_u32 s24, s58, 0x2940000
	s_addc_u32 s25, s59, 0
	s_sub_i32 s2, s18, 0x140
	s_and_b32 s2, s2, 0x7ff
	s_cmp_lt_u32 s2, 0x380
	s_cbranch_scc0 .Lcv_wbr_done
.Lcv_wbr_loop:
	s_and_b32 s12, s2, 0x1f
	s_lshr_b32 s11, s2, 5
	s_mul_i32 s13, s11, 0x40000
	s_lshl_b32 s14, s12, 7
	s_add_u32 s13, s13, s14
	s_add_u32 s40, s22, s13
	s_addc_u32 s41, s23, 0
	global_load_dwordx4 v[0:3], v50, s[40:41] nt
	s_add_u32 s40, s40, 0x1000
	s_addc_u32 s41, s41, 0
	global_load_dwordx4 v[4:7], v50, s[40:41] nt
	s_add_u32 s40, s40, 0x1000
	s_addc_u32 s41, s41, 0
	global_load_dwordx4 v[8:11], v50, s[40:41] nt
	s_add_u32 s40, s40, 0x1000
	s_addc_u32 s41, s41, 0
	global_load_dwordx4 v[14:17], v50, s[40:41] nt
	s_add_u32 s40, s40, 0x1000
	s_addc_u32 s41, s41, 0
	global_load_dwordx4 v[18:21], v50, s[40:41] nt
	s_add_u32 s40, s40, 0x1000
	s_addc_u32 s41, s41, 0
	global_load_dwordx4 v[22:25], v50, s[40:41] nt
	s_add_u32 s40, s40, 0x1000
	s_addc_u32 s41, s41, 0
	global_load_dwordx4 v[26:29], v50, s[40:41] nt
	s_add_u32 s40, s40, 0x1000
	s_addc_u32 s41, s41, 0
	global_load_dwordx4 v[30:33], v50, s[40:41] nt
	s_add_u32 s40, s40, 0x1000
	s_addc_u32 s41, s41, 0
	s_mul_i32 s13, s12, 0x1c000
	s_lshl_b32 s14, s11, 7
	s_add_u32 s13, s13, s14
	s_add_u32 s42, s24, s13
	s_addc_u32 s43, s25, 0
	s_waitcnt vmcnt(0)
	v_cvt_pk_bf16_f32 v34, v0, v4
	v_cvt_pk_bf16_f32 v35, v8, v14
	v_cvt_pk_bf16_f32 v36, v18, v22
	v_cvt_pk_bf16_f32 v37, v26, v30
	v_cvt_pk_bf16_f32 v38, v1, v5
	v_cvt_pk_bf16_f32 v39, v9, v15
	v_cvt_pk_bf16_f32 v40, v19, v23
	v_cvt_pk_bf16_f32 v41, v27, v31
	v_cvt_pk_bf16_f32 v42, v2, v6
	v_cvt_pk_bf16_f32 v43, v10, v16
	v_cvt_pk_bf16_f32 v44, v20, v24
	v_cvt_pk_bf16_f32 v45, v28, v32
	v_cvt_pk_bf16_f32 v46, v3, v7
	v_cvt_pk_bf16_f32 v47, v11, v17
	v_cvt_pk_bf16_f32 v48, v21, v25
	v_cvt_pk_bf16_f32 v49, v29, v33
	ds_write_b128 v51, v[34:37] offset:0
	ds_write_b128 v51, v[38:41] offset:144
	ds_write_b128 v51, v[42:45] offset:288
	ds_write_b128 v51, v[46:49] offset:432
	s_waitcnt lgkmcnt(0)
	ds_read_b128 v[34:37], v52 offset:0
	ds_read_b128 v[38:41], v52 offset:1152
	ds_read_b128 v[42:45], v52 offset:2304
	ds_read_b128 v[46:49], v52 offset:3456
	s_waitcnt lgkmcnt(0)
	global_store_dwordx4 v53, v[34:37], s[42:43]
	s_add_u32 s42, s42, 0x7000
	s_addc_u32 s43, s43, 0
	global_store_dwordx4 v53, v[38:41], s[42:43]
	s_add_u32 s42, s42, 0x7000
	s_addc_u32 s43, s43, 0
	global_store_dwordx4 v53, v[42:45], s[42:43]
	s_add_u32 s42, s42, 0x7000
	s_addc_u32 s43, s43, 0
	global_store_dwordx4 v53, v[46:49], s[42:43]
	s_addk_i32 s2, 0x800
	s_cmp_lt_u32 s2, 0x380
	s_cbranch_scc1 .Lcv_wbr_loop
; __device__ __forceinline__ int tidx() { int t = threadIdx.x; asm volatile("" : "+v"(t)); return t; }
; __device__ __forceinline__ float ldnt(const float* p) { return __builtin_nontemporal_load(p); }
; __device__ __forceinline__ void conv_job(const float* __restrict__ src, int ld, int K, bf16_t* dst, int Ndst, int kind, float* tile) {
;     const int tid_ = tidx();
;     const int tilesK = K >> 6, ntiles = tilesK * (Ndst >> 6);
;     const int tx = tid_ & 63, ty = tid_ >> 6;
;     const int tx2 = tid_ & 31, ty2 = tid_ >> 5;
;     float r[16];
;     int t = blockIdx.x;
;     if (t < ntiles) {
;         const int tk = t % tilesK, tn = t / tilesK, k0 = tk << 6, n0 = tn << 6;
;         const int sc = mapcol(kind, n0 + tx);
; #pragma unroll
;         for (int i = 0; i < 16; ++i) r[i] = sc >= 0 ? ldnt(src + (size_t)(k0 + ty + 4 * i) * ld + sc) : 0.f;
;     }
;     for (; t < ntiles; t += gridDim.x) {
;         const int tk = t % tilesK, tn = t / tilesK, k0 = tk << 6, n0 = tn << 6;
; #pragma unroll
;         for (int i = 0; i < 16; ++i) tile[(ty + 4 * i) * 65 + tx] = r[i];
;         __syncthreads();
;         const int tnext = t + gridDim.x;
;         if (tnext < ntiles) {
;             const int tk2 = tnext % tilesK, tn2 = tnext / tilesK, k2 = tk2 << 6, n2 = tn2 << 6;
;             const int sc = mapcol(kind, n2 + tx);
; #pragma unroll
;             for (int i = 0; i < 16; ++i) r[i] = sc >= 0 ? ldnt(src + (size_t)(k2 + ty + 4 * i) * ld + sc) : 0.f;
;         }
; #pragma unroll
;         for (int i = 0; i < 8; ++i) {
;             const int nn = ty2 + 8 * i;
;             *(unsigned*)(dst + (size_t)(n0 + nn) * K + k0 + 2 * tx2) = pack2(tile[(2 * tx2) * 65 + nn], tile[(2 * tx2 + 1) * 65 + nn]);
;         }
;         __syncthreads();
;     }
; }
; __device__ __forceinline__ void convert_layer_weights(KP p, int l, float* tile) {
;     ...
;     conv_job(p->in[I_WOUT] + (size_t)l * 1024 * 1024, 1024, 1024, (bf16_t*)(ws + OFF_WO), 1024, 0, tile);
;     for (int g = 0; g < 4; ++g)
;         conv_job(p->in[I_POOLW] + (size_t)(l * 4 + g) * 16384, 128, 128, (bf16_t*)(ws + OFF_POOLT) + g * 16384, 128, 0, tile);
.Lcv_wbr_done:
	v_mul_u32_u24_e32 v50, 0x8000, v55
	v_lshl_add_u32 v50, v54, 4, v50
	v_mul_u32_u24_e32 v51, 0x240, v54
	v_add_u32_e32 v51, v51, v56
	v_mul_u32_u24_e32 v53, 0x800, v55
	v_lshl_add_u32 v53, v54, 4, v53
	s_load_dwordx2 s[22:23], s[16:17], 0xf0
	s_mul_i32 s12, s19, 0x400000
	s_waitcnt lgkmcnt(0)
	s_add_u32 s22, s22, s12
	s_addc_u32 s23, s23, 0
	s_add_u32 s24, s58, 0x2cc0000
	s_addc_u32 s25, s59, 0
	s_sub_i32 s2, s18, 0x4c0
	s_and_b32 s2, s2, 0x7ff
	s_cmp_lt_u32 s2, 0x200
	s_cbranch_scc0 .Lcv_wout_done
.Lcv_wout_loop:
	s_and_b32 s11, s2, 0xf
	s_lshr_b32 s12, s2, 4
	s_mul_i32 s13, s11, 0x40000
	s_lshl_b32 s14, s12, 7
	s_add_u32 s13, s13, s14
	s_add_u32 s40, s22, s13
	s_addc_u32 s41, s23, 0
	global_load_dwordx4 v[0:3], v50, s[40:41] nt
	s_add_u32 s40, s40, 0x1000
	s_addc_u32 s41, s41, 0
	global_load_dwordx4 v[4:7], v50, s[40:41] nt
	s_add_u32 s40, s40, 0x1000
	s_addc_u32 s41, s41, 0
	global_load_dwordx4 v[8:11], v50, s[40:41] nt
	s_add_u32 s40, s40, 0x1000
	s_addc_u32 s41, s41, 0
	global_load_dwordx4 v[14:17], v50, s[40:41] nt
	s_add_u32 s40, s40, 0x1000
	s_addc_u32 s41, s41, 0
	global_load_dwordx4 v[18:21], v50, s[40:41] nt
	s_add_u32 s40, s40, 0x1000
	s_addc_u32 s41, s41, 0
	global_load_dwordx4 v[22:25], v50, s[40:41] nt
	s_add_u32 s40, s40, 0x1000
	s_addc_u32 s41, s41, 0
	global_load_dwordx4 v[26:29], v50, s[40:41] nt
	s_add_u32 s40, s40, 0x1000
	s_addc_u32 s41, s41, 0
	global_load_dwordx4 v[30:33], v50, s[40:41] nt
	s_add_u32 s40, s40, 0x1000
	s_addc_u32 s41, s41, 0
	s_mul_i32 s13, s12, 0x10000
	s_lshl_b32 s14, s11, 7
	s_add_u32 s13, s13, s14
	s_add_u32 s42, s24, s13
	s_addc_u32 s43, s25, 0
	s_waitcnt vmcnt(0)
	v_cvt_pk_bf16_f32 v34, v0, v4
	v_cvt_pk_bf16_f32 v35, v8, v14
	v_cvt_pk_bf16_f32 v36, v18, v22
	v_cvt_pk_bf16_f32 v37, v26, v30
	v_cvt_pk_bf16_f32 v38, v1, v5
	v_cvt_pk_bf16_f32 v39, v9, v15
	v_cvt_pk_bf16_f32 v40, v19, v23
	v_cvt_pk_bf16_f32 v41, v27, v31
	v_cvt_pk_bf16_f32 v42, v2, v6
	v_cvt_pk_bf16_f32 v43, v10, v16
	v_cvt_pk_bf16_f32 v44, v20, v24
	v_cvt_pk_bf16_f32 v45, v28, v32
	v_cvt_pk_bf16_f32 v46, v3, v7
	v_cvt_pk_bf16_f32 v47, v11, v17
	v_cvt_pk_bf16_f32 v48, v21, v25
	v_cvt_pk_bf16_f32 v49, v29, v33
	ds_write_b128 v51, v[34:37] offset:0
	ds_write_b128 v51, v[38:41] offset:144
	ds_write_b128 v51, v[42:45] offset:288
	ds_write_b128 v51, v[46:49] offset:432
	s_waitcnt lgkmcnt(0)
	ds_read_b128 v[34:37], v52 offset:0
	ds_read_b128 v[38:41], v52 offset:1152
	ds_read_b128 v[42:45], v52 offset:2304
	ds_read_b128 v[46:49], v52 offset:3456
	s_waitcnt lgkmcnt(0)
	global_store_dwordx4 v53, v[34:37], s[42:43]
	s_add_u32 s42, s42, 0x4000
	s_addc_u32 s43, s43, 0
	global_store_dwordx4 v53, v[38:41], s[42:43]
	s_add_u32 s42, s42, 0x4000
	s_addc_u32 s43, s43, 0
	global_store_dwordx4 v53, v[42:45], s[42:43]
	s_add_u32 s42, s42, 0x4000
	s_addc_u32 s43, s43, 0
	global_store_dwordx4 v53, v[46:49], s[42:43]
	s_addk_i32 s2, 0x800
	s_cmp_lt_u32 s2, 0x200
	s_cbranch_scc1 .Lcv_wout_loop
.Lcv_wout_done:
	v_mul_u32_u24_e32 v50, 0x1000, v55
	v_lshl_add_u32 v50, v54, 4, v50
	v_mul_u32_u24_e32 v51, 0x240, v54
	v_add_u32_e32 v51, v51, v56
	v_mul_u32_u24_e32 v53, 0x100, v55
	v_lshl_add_u32 v53, v54, 4, v53
	s_load_dwordx2 s[22:23], s[16:17], 0xb0
	s_mul_i32 s12, s19, 0x40000
	s_waitcnt lgkmcnt(0)
	s_add_u32 s22, s22, s12
	s_addc_u32 s23, s23, 0
	s_add_u32 s24, s58, 0x2ec0000
	s_addc_u32 s25, s59, 0
	s_sub_i32 s2, s18, 0x6c0
	s_and_b32 s2, s2, 0x7ff
	s_cmp_lt_u32 s2, 0x8
	s_cbranch_scc0 .Lcv_pool0_done
.Lcv_pool0_loop:
	s_and_b32 s11, s2, 0x1
	s_lshr_b32 s12, s2, 1
	s_mul_i32 s13, s11, 0x8000
	s_lshl_b32 s14, s12, 7
	s_add_u32 s13, s13, s14
	s_add_u32 s40, s22, s13
	s_addc_u32 s41, s23, 0
	global_load_dwordx4 v[0:3], v50, s[40:41] nt
	s_add_u32 s40, s40, 0x200
	s_addc_u32 s41, s41, 0
	global_load_dwordx4 v[4:7], v50, s[40:41] nt
	s_add_u32 s40, s40, 0x200
	s_addc_u32 s41, s41, 0
	global_load_dwordx4 v[8:11], v50, s[40:41] nt
	s_add_u32 s40, s40, 0x200
	s_addc_u32 s41, s41, 0
	global_load_dwordx4 v[14:17], v50, s[40:41] nt
	s_add_u32 s40, s40, 0x200
	s_addc_u32 s41, s41, 0
	global_load_dwordx4 v[18:21], v50, s[40:41] nt
	s_add_u32 s40, s40, 0x200
	s_addc_u32 s41, s41, 0
	global_load_dwordx4 v[22:25], v50, s[40:41] nt
	s_add_u32 s40, s40, 0x200
	s_addc_u32 s41, s41, 0
	global_load_dwordx4 v[26:29], v50, s[40:41] nt
	s_add_u32 s40, s40, 0x200
	s_addc_u32 s41, s41, 0
	global_load_dwordx4 v[30:33], v50, s[40:41] nt
	s_add_u32 s40, s40, 0x200
	s_addc_u32 s41, s41, 0
	s_mul_i32 s13, s12, 0x2000
	s_lshl_b32 s14, s11, 7
	s_add_u32 s13, s13, s14
	s_add_u32 s42, s24, s13
	s_addc_u32 s43, s25, 0
	s_waitcnt vmcnt(0)
	v_cvt_pk_bf16_f32 v34, v0, v4
	v_cvt_pk_bf16_f32 v35, v8, v14
	v_cvt_pk_bf16_f32 v36, v18, v22
	v_cvt_pk_bf16_f32 v37, v26, v30
	v_cvt_pk_bf16_f32 v38, v1, v5
	v_cvt_pk_bf16_f32 v39, v9, v15
	v_cvt_pk_bf16_f32 v40, v19, v23
	v_cvt_pk_bf16_f32 v41, v27, v31
	v_cvt_pk_bf16_f32 v42, v2, v6
	v_cvt_pk_bf16_f32 v43, v10, v16
	v_cvt_pk_bf16_f32 v44, v20, v24
	v_cvt_pk_bf16_f32 v45, v28, v32
	v_cvt_pk_bf16_f32 v46, v3, v7
	v_cvt_pk_bf16_f32 v47, v11, v17
	v_cvt_pk_bf16_f32 v48, v21, v25
	v_cvt_pk_bf16_f32 v49, v29, v33
	ds_write_b128 v51, v[34:37] offset:0
	ds_write_b128 v51, v[38:41] offset:144
	ds_write_b128 v51, v[42:45] offset:288
	ds_write_b128 v51, v[46:49] offset:432
	s_waitcnt lgkmcnt(0)
	ds_read_b128 v[34:37], v52 offset:0
	ds_read_b128 v[38:41], v52 offset:1152
	ds_read_b128 v[42:45], v52 offset:2304
	ds_read_b128 v[46:49], v52 offset:3456
	s_waitcnt lgkmcnt(0)
	global_store_dwordx4 v53, v[34:37], s[42:43]
	s_add_u32 s42, s42, 0x800
	s_addc_u32 s43, s43, 0
	global_store_dwordx4 v53, v[38:41], s[42:43]
	s_add_u32 s42, s42, 0x800
	s_addc_u32 s43, s43, 0
	global_store_dwordx4 v53, v[42:45], s[42:43]
	s_add_u32 s42, s42, 0x800
	s_addc_u32 s43, s43, 0
	global_store_dwordx4 v53, v[46:49], s[42:43]
	s_addk_i32 s2, 0x800
	s_cmp_lt_u32 s2, 0x8
	s_cbranch_scc1 .Lcv_pool0_loop
.Lcv_pool0_done:
	v_mul_u32_u24_e32 v50, 0x1000, v55
	v_lshl_add_u32 v50, v54, 4, v50
	v_mul_u32_u24_e32 v51, 0x240, v54
	v_add_u32_e32 v51, v51, v56
	v_mul_u32_u24_e32 v53, 0x100, v55
	v_lshl_add_u32 v53, v54, 4, v53
	s_load_dwordx2 s[22:23], s[16:17], 0xb0
	s_mul_i32 s12, s19, 0x40000
	s_add_u32 s12, s12, 0x10000
	s_waitcnt lgkmcnt(0)
	s_add_u32 s22, s22, s12
	s_addc_u32 s23, s23, 0
	s_add_u32 s24, s58, 0x2ec8000
	s_addc_u32 s25, s59, 0
	s_sub_i32 s2, s18, 0x6c8
	s_and_b32 s2, s2, 0x7ff
	s_cmp_lt_u32 s2, 0x8
	s_cbranch_scc0 .Lcv_pool1_done

; __device__ __forceinline__ void convert_layer_weights(KP p, int l, float* tile) {
;     ...
;     for (int g = 0; g < 4; ++g)
;         conv_job(p->in[I_POOLW] + (size_t)(l * 4 + g) * 16384, 128, 128, (bf16_t*)(ws + OFF_POOLT) + g * 16384, 128, 0, tile);
.Lcv_pool1_done:
	v_mul_u32_u24_e32 v50, 0x1000, v55
	v_lshl_add_u32 v50, v54, 4, v50
	v_mul_u32_u24_e32 v51, 0x240, v54
	v_add_u32_e32 v51, v51, v56
	v_mul_u32_u24_e32 v53, 0x100, v55
	v_lshl_add_u32 v53, v54, 4, v53
	s_load_dwordx2 s[22:23], s[16:17], 0xb0
	s_mul_i32 s12, s19, 0x40000
	s_add_u32 s12, s12, 0x20000
	s_waitcnt lgkmcnt(0)
	s_add_u32 s22, s22, s12
	s_addc_u32 s23, s23, 0
	s_add_u32 s24, s58, 0x2ed0000
	s_addc_u32 s25, s59, 0
	s_sub_i32 s2, s18, 0x6d0
	s_and_b32 s2, s2, 0x7ff
	s_cmp_lt_u32 s2, 0x8
	s_cbranch_scc0 .Lcv_pool2_done

; __device__ __forceinline__ void convert_layer_weights(KP p, int l, float* tile) {
;     ...
;     for (int g = 0; g < 4; ++g)
;         conv_job(p->in[I_POOLW] + (size_t)(l * 4 + g) * 16384, 128, 128, (bf16_t*)(ws + OFF_POOLT) + g * 16384, 128, 0, tile);
.Lcv_pool2_done:
	v_mul_u32_u24_e32 v50, 0x1000, v55
	v_lshl_add_u32 v50, v54, 4, v50
	v_mul_u32_u24_e32 v51, 0x240, v54
	v_add_u32_e32 v51, v51, v56
	v_mul_u32_u24_e32 v53, 0x100, v55
	v_lshl_add_u32 v53, v54, 4, v53
	s_load_dwordx2 s[22:23], s[16:17], 0xb0
	s_mul_i32 s12, s19, 0x40000
	s_add_u32 s12, s12, 0x30000
	s_waitcnt lgkmcnt(0)
	s_add_u32 s22, s22, s12
	s_addc_u32 s23, s23, 0
	s_add_u32 s24, s58, 0x2ed8000
	s_addc_u32 s25, s59, 0
	s_sub_i32 s2, s18, 0x6d8
	s_and_b32 s2, s2, 0x7ff
	s_cmp_lt_u32 s2, 0x8
	s_cbranch_scc0 .Lcv_pool3_done

; __device__ __forceinline__ void convert_layer_weights(KP p, int l, float* tile) {
;     ...
;     for (int g = 0; g < 4; ++g)
;         conv_job(p->in[I_POOLW] + (size_t)(l * 4 + g) * 16384, 128, 128, (bf16_t*)(ws + OFF_POOLT) + g * 16384, 128, 0, tile);
;     conv_job(p->in[I_WUP] + (size_t)l * 64 * 512, 512, 64, (bf16_t*)(ws + OFF_WUP), 512, 0, tile);
;     conv_job(p->in[I_AUP] + (size_t)l * 64 * 512, 512, 64, (bf16_t*)(ws + OFF_AUP), 512, 0, tile);
.Lcv_pool3_done:
	v_mul_u32_u24_e32 v50, 0x4000, v55
	v_lshl_add_u32 v50, v54, 4, v50
	v_mul_u32_u24_e32 v51, 0x240, v54
	v_add_u32_e32 v51, v51, v56
	v_mul_u32_u24_e32 v53, 0x80, v55
	v_lshl_add_u32 v53, v54, 4, v53
	s_load_dwordx2 s[22:23], s[16:17], 0x68
	s_mul_i32 s12, s19, 0x20000
	s_waitcnt lgkmcnt(0)
	s_add_u32 s22, s22, s12
	s_addc_u32 s23, s23, 0
	s_add_u32 s24, s58, 0x2ee0000
	s_addc_u32 s25, s59, 0
	s_sub_i32 s2, s18, 0x6e0
	s_and_b32 s2, s2, 0x7ff
	s_cmp_lt_u32 s2, 0x10
	s_cbranch_scc0 .Lcv_wup_done
.Lcv_wup_loop:
	s_and_b32 s11, s2, 0x0
	s_lshr_b32 s12, s2, 0
	s_mul_i32 s13, s11, 0x20000
	s_lshl_b32 s14, s12, 7
	s_add_u32 s13, s13, s14
	s_add_u32 s40, s22, s13
	s_addc_u32 s41, s23, 0
	global_load_dwordx4 v[0:3], v50, s[40:41] nt
	s_add_u32 s40, s40, 0x800
	s_addc_u32 s41, s41, 0
	global_load_dwordx4 v[4:7], v50, s[40:41] nt
	s_add_u32 s40, s40, 0x800
	s_addc_u32 s41, s41, 0
	global_load_dwordx4 v[8:11], v50, s[40:41] nt
	s_add_u32 s40, s40, 0x800
	s_addc_u32 s41, s41, 0
	global_load_dwordx4 v[14:17], v50, s[40:41] nt
	s_add_u32 s40, s40, 0x800
	s_addc_u32 s41, s41, 0
	global_load_dwordx4 v[18:21], v50, s[40:41] nt
	s_add_u32 s40, s40, 0x800
	s_addc_u32 s41, s41, 0
	global_load_dwordx4 v[22:25], v50, s[40:41] nt
	s_add_u32 s40, s40, 0x800
	s_addc_u32 s41, s41, 0
	global_load_dwordx4 v[26:29], v50, s[40:41] nt
	s_add_u32 s40, s40, 0x800
	s_addc_u32 s41, s41, 0
	global_load_dwordx4 v[30:33], v50, s[40:41] nt
	s_add_u32 s40, s40, 0x800
	s_addc_u32 s41, s41, 0
	s_mul_i32 s13, s12, 0x1000
	s_lshl_b32 s14, s11, 7
	s_add_u32 s13, s13, s14
	s_add_u32 s42, s24, s13
	s_addc_u32 s43, s25, 0
	s_waitcnt vmcnt(0)
	v_cvt_pk_bf16_f32 v34, v0, v4
	v_cvt_pk_bf16_f32 v35, v8, v14
	v_cvt_pk_bf16_f32 v36, v18, v22
	v_cvt_pk_bf16_f32 v37, v26, v30
	v_cvt_pk_bf16_f32 v38, v1, v5
	v_cvt_pk_bf16_f32 v39, v9, v15
	v_cvt_pk_bf16_f32 v40, v19, v23
	v_cvt_pk_bf16_f32 v41, v27, v31
	v_cvt_pk_bf16_f32 v42, v2, v6
	v_cvt_pk_bf16_f32 v43, v10, v16
	v_cvt_pk_bf16_f32 v44, v20, v24
	v_cvt_pk_bf16_f32 v45, v28, v32
	v_cvt_pk_bf16_f32 v46, v3, v7
	v_cvt_pk_bf16_f32 v47, v11, v17
	v_cvt_pk_bf16_f32 v48, v21, v25
	v_cvt_pk_bf16_f32 v49, v29, v33
	ds_write_b128 v51, v[34:37] offset:0
	ds_write_b128 v51, v[38:41] offset:144
	ds_write_b128 v51, v[42:45] offset:288
	ds_write_b128 v51, v[46:49] offset:432
	s_waitcnt lgkmcnt(0)
	ds_read_b128 v[34:37], v52 offset:0
	ds_read_b128 v[38:41], v52 offset:1152
	ds_read_b128 v[42:45], v52 offset:2304
	ds_read_b128 v[46:49], v52 offset:3456
	s_waitcnt lgkmcnt(0)
	global_store_dwordx4 v53, v[34:37], s[42:43]
	s_add_u32 s42, s42, 0x400
	s_addc_u32 s43, s43, 0
	global_store_dwordx4 v53, v[38:41], s[42:43]
	s_add_u32 s42, s42, 0x400
	s_addc_u32 s43, s43, 0
	global_store_dwordx4 v53, v[42:45], s[42:43]
	s_add_u32 s42, s42, 0x400
	s_addc_u32 s43, s43, 0
	global_store_dwordx4 v53, v[46:49], s[42:43]
	s_addk_i32 s2, 0x800
	s_cmp_lt_u32 s2, 0x10
	s_cbranch_scc1 .Lcv_wup_loop
.Lcv_wup_done:
	v_mul_u32_u24_e32 v50, 0x4000, v55
	v_lshl_add_u32 v50, v54, 4, v50
	v_mul_u32_u24_e32 v51, 0x240, v54
	v_add_u32_e32 v51, v51, v56
	v_mul_u32_u24_e32 v53, 0x80, v55
	v_lshl_add_u32 v53, v54, 4, v53
	s_load_dwordx2 s[22:23], s[16:17], 0x78
	s_mul_i32 s12, s19, 0x20000
	s_waitcnt lgkmcnt(0)
	s_add_u32 s22, s22, s12
	s_addc_u32 s23, s23, 0
	s_add_u32 s24, s58, 0x2ef0000
	s_addc_u32 s25, s59, 0
	s_sub_i32 s2, s18, 0x6f0
	s_and_b32 s2, s2, 0x7ff
	s_cmp_lt_u32 s2, 0x10
	s_cbranch_scc0 .Lcv_aup_done

; __device__ __forceinline__ int tidx() { int t = threadIdx.x; asm volatile("" : "+v"(t)); return t; }
; __device__ __forceinline__ float ldnt(const float* p) { return __builtin_nontemporal_load(p); }
; __device__ __forceinline__ void conv_job(const float* __restrict__ src, int ld, int K, bf16_t* dst, int Ndst, int kind, float* tile) {
;     const int tid_ = tidx();
;     const int tilesK = K >> 6, ntiles = tilesK * (Ndst >> 6);
;     const int tx = tid_ & 63, ty = tid_ >> 6;
;     const int tx2 = tid_ & 31, ty2 = tid_ >> 5;
;     float r[16];
;     int t = blockIdx.x;
;     if (t < ntiles) {
;         const int tk = t % tilesK, tn = t / tilesK, k0 = tk << 6, n0 = tn << 6;
;         const int sc = mapcol(kind, n0 + tx);
; #pragma unroll
;         for (int i = 0; i < 16; ++i) r[i] = sc >= 0 ? ldnt(src + (size_t)(k0 + ty + 4 * i) * ld + sc) : 0.f;
;     }
;     for (; t < ntiles; t += gridDim.x) {
;         const int tk = t % tilesK, tn = t / tilesK, k0 = tk << 6, n0 = tn << 6;
; #pragma unroll
;         for (int i = 0; i < 16; ++i) tile[(ty + 4 * i) * 65 + tx] = r[i];
;         __syncthreads();
;         const int tnext = t + gridDim.x;
;         if (tnext < ntiles) {
;             const int tk2 = tnext % tilesK, tn2 = tnext / tilesK, k2 = tk2 << 6, n2 = tn2 << 6;
;             const int sc = mapcol(kind, n2 + tx);
; #pragma unroll
;             for (int i = 0; i < 16; ++i) r[i] = sc >= 0 ? ldnt(src + (size_t)(k2 + ty + 4 * i) * ld + sc) : 0.f;
;         }
; #pragma unroll
;         for (int i = 0; i < 8; ++i) {
;             const int nn = ty2 + 8 * i;
;             *(unsigned*)(dst + (size_t)(n0 + nn) * K + k0 + 2 * tx2) = pack2(tile[(2 * tx2) * 65 + nn], tile[(2 * tx2 + 1) * 65 + nn]);
;         }
;         __syncthreads();
;     }
; }
; __device__ __forceinline__ void convert_layer_weights(KP p, int l, float* tile) {
;     ...
;     conv_job(p->in[I_WUP] + (size_t)l * 64 * 512, 512, 64, (bf16_t*)(ws + OFF_WUP), 512, 0, tile);
;     conv_job(p->in[I_AUP] + (size_t)l * 64 * 512, 512, 64, (bf16_t*)(ws + OFF_AUP), 512, 0, tile);
;     conv_job(p->in[I_GUP] + (size_t)l * 128 * 512, 512, 128, (bf16_t*)(ws + OFF_GUP), 512, 0, tile);
.Lcv_aup_done:
	v_mul_u32_u24_e32 v50, 0x4000, v55
	v_lshl_add_u32 v50, v54, 4, v50
	v_mul_u32_u24_e32 v51, 0x240, v54
	v_add_u32_e32 v51, v51, v56
	v_mul_u32_u24_e32 v53, 0x100, v55
	v_lshl_add_u32 v53, v54, 4, v53
	s_load_dwordx2 s[22:23], s[16:17], 0x80
	s_mul_i32 s12, s19, 0x40000
	s_waitcnt lgkmcnt(0)
	s_add_u32 s22, s22, s12
	s_addc_u32 s23, s23, 0
	s_add_u32 s24, s58, 0x2f00000
	s_addc_u32 s25, s59, 0
	s_sub_i32 s2, s18, 0x700
	s_and_b32 s2, s2, 0x7ff
	s_cmp_lt_u32 s2, 0x20
	s_cbranch_scc0 .Lcv_gup_done
.Lcv_gup_loop:
	s_and_b32 s11, s2, 0x1
	s_lshr_b32 s12, s2, 1
	s_mul_i32 s13, s11, 0x20000
	s_lshl_b32 s14, s12, 7
	s_add_u32 s13, s13, s14
	s_add_u32 s40, s22, s13
	s_addc_u32 s41, s23, 0
	global_load_dwordx4 v[0:3], v50, s[40:41] nt
	s_add_u32 s40, s40, 0x800
	s_addc_u32 s41, s41, 0
	global_load_dwordx4 v[4:7], v50, s[40:41] nt
	s_add_u32 s40, s40, 0x800
	s_addc_u32 s41, s41, 0
	global_load_dwordx4 v[8:11], v50, s[40:41] nt
	s_add_u32 s40, s40, 0x800
	s_addc_u32 s41, s41, 0
	global_load_dwordx4 v[14:17], v50, s[40:41] nt
	s_add_u32 s40, s40, 0x800
	s_addc_u32 s41, s41, 0
	global_load_dwordx4 v[18:21], v50, s[40:41] nt
	s_add_u32 s40, s40, 0x800
	s_addc_u32 s41, s41, 0
	global_load_dwordx4 v[22:25], v50, s[40:41] nt
	s_add_u32 s40, s40, 0x800
	s_addc_u32 s41, s41, 0
	global_load_dwordx4 v[26:29], v50, s[40:41] nt
	s_add_u32 s40, s40, 0x800
	s_addc_u32 s41, s41, 0
	global_load_dwordx4 v[30:33], v50, s[40:41] nt
	s_add_u32 s40, s40, 0x800
	s_addc_u32 s41, s41, 0
	s_mul_i32 s13, s12, 0x2000
	s_lshl_b32 s14, s11, 7
	s_add_u32 s13, s13, s14
	s_add_u32 s42, s24, s13
	s_addc_u32 s43, s25, 0
	s_waitcnt vmcnt(0)
	v_cvt_pk_bf16_f32 v34, v0, v4
	v_cvt_pk_bf16_f32 v35, v8, v14
	v_cvt_pk_bf16_f32 v36, v18, v22
	v_cvt_pk_bf16_f32 v37, v26, v30
	v_cvt_pk_bf16_f32 v38, v1, v5
	v_cvt_pk_bf16_f32 v39, v9, v15
	v_cvt_pk_bf16_f32 v40, v19, v23
	v_cvt_pk_bf16_f32 v41, v27, v31
	v_cvt_pk_bf16_f32 v42, v2, v6
	v_cvt_pk_bf16_f32 v43, v10, v16
	v_cvt_pk_bf16_f32 v44, v20, v24
	v_cvt_pk_bf16_f32 v45, v28, v32
	v_cvt_pk_bf16_f32 v46, v3, v7
	v_cvt_pk_bf16_f32 v47, v11, v17
	v_cvt_pk_bf16_f32 v48, v21, v25
	v_cvt_pk_bf16_f32 v49, v29, v33
	ds_write_b128 v51, v[34:37] offset:0
	ds_write_b128 v51, v[38:41] offset:144
	ds_write_b128 v51, v[42:45] offset:288
	ds_write_b128 v51, v[46:49] offset:432
	s_waitcnt lgkmcnt(0)
	ds_read_b128 v[34:37], v52 offset:0
	ds_read_b128 v[38:41], v52 offset:1152
	ds_read_b128 v[42:45], v52 offset:2304
	ds_read_b128 v[46:49], v52 offset:3456
	s_waitcnt lgkmcnt(0)
	global_store_dwordx4 v53, v[34:37], s[42:43]
	s_add_u32 s42, s42, 0x800
	s_addc_u32 s43, s43, 0
	global_store_dwordx4 v53, v[38:41], s[42:43]
	s_add_u32 s42, s42, 0x800
	s_addc_u32 s43, s43, 0
	global_store_dwordx4 v53, v[42:45], s[42:43]
	s_add_u32 s42, s42, 0x800
	s_addc_u32 s43, s43, 0
	global_store_dwordx4 v53, v[46:49], s[42:43]
	s_addk_i32 s2, 0x800
	s_cmp_lt_u32 s2, 0x20
	s_cbranch_scc1 .Lcv_gup_loop
.Lcv_gup_done:
	s_waitcnt vmcnt(0)
.LBB0_1475:
	s_mov_b64 s[14:15], 0
